# v26 + nt hints extended: all transpose tile loads, combine partial/LSE reads, final LN row reads
# baseline (speedup 1.0000x reference)
; #define LAS __attribute__((address_space(3)))
; __device__ __forceinline__ void transpose_item(const float* W, int K, int N, bf16_t* WT, int mode, LAS float* scr, int item, int lane, const float* gvec, const float* bvec, float* csp, int nblk, int nmagic) {
;     const int kb = (item * nmagic) >> 20, nb = item - kb * nblk, k0 = 64 * kb, n0 = 64 * nb;
;     int r0 = n0;
;     if (mode == 1) { const int bj = n0 / DFF, rem = n0 % DFF; r0 = 256 * (rem / 128) + 128 * bj + (rem % 128); }
;     const int rr = lane >> 4, q = lane & 15;
;     f32x4 t[16];
; #pragma unroll
;     for (int i = 0; i < 16; ++i) t[i] = *(const f32x4*)(W + (size_t)(k0 + 4 * i + rr) * N + n0 + 4 * q);
; #pragma unroll
;     for (int i = 0; i < 16; ++i) { LAS float* d = scr + (4 * i + rr) * 65 + 4 * q; d[0] = t[i][0]; d[1] = t[i][1]; d[2] = t[i][2]; d[3] = t[i][3]; }
.LBB0_65:
	s_lshl_b32 s26, s0, 6
	v_add_u32_e32 v55, s26, v19
	s_ashr_i32 s3, s2, 31
	v_lshl_add_u64 v[48:49], s[2:3], 2, v[36:37]
	v_mad_u64_u32 v[2:3], s[2:3], v55, s35, 0
	s_waitcnt lgkmcnt(0)
	v_ashrrev_i32_e32 v5, 31, v55
	v_mov_b32_e32 v4, v3
	v_mad_u64_u32 v[4:5], s[2:3], v5, s35, v[4:5]
	v_add_u32_e32 v10, 8, v55
	v_mov_b32_e32 v3, v4
	v_add_u32_e32 v4, 4, v55
	v_ashrrev_i32_e32 v13, 31, v10
	v_mad_u64_u32 v[10:11], s[2:3], v10, s35, 0
	v_ashrrev_i32_e32 v7, 31, v4
	v_mad_u64_u32 v[4:5], s[2:3], v4, s35, 0
	v_mov_b32_e32 v12, v11
	v_mov_b32_e32 v6, v5
	v_mad_u64_u32 v[12:13], s[2:3], v13, s35, v[12:13]
	v_mad_u64_u32 v[6:7], s[2:3], v7, s35, v[6:7]
	v_mov_b32_e32 v11, v12
	v_add_u32_e32 v12, 12, v55
	v_add_u32_e32 v44, 16, v55
	v_mov_b32_e32 v5, v6
	v_ashrrev_i32_e32 v15, 31, v12
	v_mad_u64_u32 v[12:13], s[2:3], v12, s35, 0
	v_ashrrev_i32_e32 v47, 31, v44
	v_mad_u64_u32 v[44:45], s[2:3], v44, s35, 0
	v_lshl_add_u64 v[2:3], v[2:3], 2, v[48:49]
	v_lshl_add_u64 v[6:7], v[4:5], 2, v[48:49]
	v_mov_b32_e32 v14, v13
	v_mov_b32_e32 v46, v45
	global_load_dwordx4 v[2:5], v[2:3], off nt
	s_nop 0
	global_load_dwordx4 v[6:9], v[6:7], off nt
	v_mad_u64_u32 v[14:15], s[2:3], v15, s35, v[14:15]
	v_mad_u64_u32 v[46:47], s[2:3], v47, s35, v[46:47]
	v_mov_b32_e32 v13, v14
	v_mov_b32_e32 v45, v46
	v_add_u32_e32 v46, 20, v55
	v_add_u32_e32 v60, 24, v55
	v_lshl_add_u64 v[10:11], v[10:11], 2, v[48:49]
	v_lshl_add_u64 v[14:15], v[12:13], 2, v[48:49]
	v_ashrrev_i32_e32 v57, 31, v46
	v_mad_u64_u32 v[46:47], s[2:3], v46, s35, 0
	v_ashrrev_i32_e32 v63, 31, v60
	v_mad_u64_u32 v[60:61], s[2:3], v60, s35, 0
	global_load_dwordx4 v[10:13], v[10:11], off nt
	s_nop 0
	global_load_dwordx4 v[14:17], v[14:15], off nt
	v_mov_b32_e32 v56, v47
	v_mov_b32_e32 v62, v61
	v_mad_u64_u32 v[56:57], s[2:3], v57, s35, v[56:57]
	v_mad_u64_u32 v[62:63], s[2:3], v63, s35, v[62:63]
	v_mov_b32_e32 v47, v56
	v_mov_b32_e32 v61, v62
	v_add_u32_e32 v62, 28, v55
	v_add_u32_e32 v68, 32, v55
	v_lshl_add_u64 v[44:45], v[44:45], 2, v[48:49]
	v_lshl_add_u64 v[56:57], v[46:47], 2, v[48:49]
	v_ashrrev_i32_e32 v65, 31, v62
	v_mad_u64_u32 v[62:63], s[2:3], v62, s35, 0
	v_ashrrev_i32_e32 v71, 31, v68
	v_mad_u64_u32 v[68:69], s[2:3], v68, s35, 0
	global_load_dwordx4 v[44:47], v[44:45], off nt
	s_nop 0
	global_load_dwordx4 v[56:59], v[56:57], off nt
	v_mov_b32_e32 v64, v63
	v_mov_b32_e32 v70, v69
	v_mad_u64_u32 v[64:65], s[2:3], v65, s35, v[64:65]
	v_mad_u64_u32 v[70:71], s[2:3], v71, s35, v[70:71]
	v_mov_b32_e32 v63, v64
	v_mov_b32_e32 v69, v70
	v_add_u32_e32 v70, 36, v55
	v_add_u32_e32 v76, 40, v55
	v_lshl_add_u64 v[60:61], v[60:61], 2, v[48:49]
	v_lshl_add_u64 v[64:65], v[62:63], 2, v[48:49]
	v_ashrrev_i32_e32 v73, 31, v70
	v_mad_u64_u32 v[70:71], s[2:3], v70, s35, 0
	v_ashrrev_i32_e32 v79, 31, v76
	v_mad_u64_u32 v[76:77], s[2:3], v76, s35, 0
	global_load_dwordx4 v[60:63], v[60:61], off nt
	s_nop 0
	global_load_dwordx4 v[64:67], v[64:65], off nt
	v_mov_b32_e32 v72, v71
	v_mov_b32_e32 v78, v77
	v_mad_u64_u32 v[72:73], s[2:3], v73, s35, v[72:73]
	v_mad_u64_u32 v[78:79], s[2:3], v79, s35, v[78:79]
	v_mov_b32_e32 v71, v72
	v_mov_b32_e32 v77, v78
	v_add_u32_e32 v78, 44, v55
	v_add_u32_e32 v84, 48, v55
	v_lshl_add_u64 v[68:69], v[68:69], 2, v[48:49]
	v_lshl_add_u64 v[72:73], v[70:71], 2, v[48:49]
	v_ashrrev_i32_e32 v81, 31, v78
	v_mad_u64_u32 v[78:79], s[2:3], v78, s35, 0
	v_ashrrev_i32_e32 v87, 31, v84
	v_mad_u64_u32 v[84:85], s[2:3], v84, s35, 0
	global_load_dwordx4 v[68:71], v[68:69], off nt
	s_nop 0
	global_load_dwordx4 v[72:75], v[72:73], off nt
	v_mov_b32_e32 v80, v79
	v_mov_b32_e32 v86, v85
	v_mad_u64_u32 v[80:81], s[2:3], v81, s35, v[80:81]
	v_mad_u64_u32 v[86:87], s[2:3], v87, s35, v[86:87]
	v_mov_b32_e32 v79, v80
	v_mov_b32_e32 v85, v86
	v_add_u32_e32 v86, 52, v55
	v_lshl_add_u64 v[76:77], v[76:77], 2, v[48:49]
	v_lshl_add_u64 v[80:81], v[78:79], 2, v[48:49]
	v_ashrrev_i32_e32 v89, 31, v86
	v_mad_u64_u32 v[86:87], s[2:3], v86, s35, 0
	global_load_dwordx4 v[76:79], v[76:77], off nt
	s_nop 0
	global_load_dwordx4 v[80:83], v[80:81], off nt
	v_mov_b32_e32 v88, v87
	v_mad_u64_u32 v[88:89], s[2:3], v89, s35, v[88:89]
	v_add_u32_e32 v92, 56, v55
	v_mov_b32_e32 v87, v88
	v_ashrrev_i32_e32 v95, 31, v92
	v_mad_u64_u32 v[92:93], s[2:3], v92, s35, 0
	v_lshl_add_u64 v[84:85], v[84:85], 2, v[48:49]
	v_lshl_add_u64 v[88:89], v[86:87], 2, v[48:49]
	v_mov_b32_e32 v94, v93
	v_add_u32_e32 v55, 60, v55
	global_load_dwordx4 v[84:87], v[84:85], off nt
	s_nop 0
	global_load_dwordx4 v[88:91], v[88:89], off nt
	v_mad_u64_u32 v[94:95], s[2:3], v95, s35, v[94:95]
	v_mad_u64_u32 v[96:97], s[2:3], v55, s35, 0
	v_mov_b32_e32 v93, v94
	v_ashrrev_i32_e32 v99, 31, v55
	v_mov_b32_e32 v98, v97
	v_lshl_add_u64 v[92:93], v[92:93], 2, v[48:49]
	v_mad_u64_u32 v[98:99], s[2:3], v99, s35, v[98:99]
	global_load_dwordx4 v[92:95], v[92:93], off nt
	v_mov_b32_e32 v97, v98
	v_lshl_add_u64 v[48:49], v[96:97], 2, v[48:49]
	global_load_dwordx4 v[96:99], v[48:49], off nt
	s_waitcnt vmcnt(15)
; #define LAS __attribute__((address_space(3)))
; #define LDS_WAIT() asm volatile("s_waitcnt lgkmcnt(0)" ::: "memory")
; __device__ __forceinline__ void transpose_item(const float* W, int K, int N, bf16_t* WT, int mode, LAS float* scr, int item, int lane, const float* gvec, const float* bvec, float* csp, int nblk, int nmagic) {
;     ...
;     for (int i = 0; i < 16; ++i) { LAS float* d = scr + (4 * i + rr) * 65 + 4 * q; d[0] = t[i][0]; d[1] = t[i][1]; d[2] = t[i][2]; d[3] = t[i][3]; }
;     LDS_WAIT(); asm volatile("" ::: "memory");
;     const int c = lane & 7;
;     if (csp) {
;         f32x4 g0 = (f32x4){1.f, 1.f, 1.f, 1.f}, g1 = g0, b0 = (f32x4){0.f, 0.f, 0.f, 0.f}, b1 = b0;
;         if (gvec) { g0 = *(const f32x4*)(gvec + k0 + 8 * c); g1 = *(const f32x4*)(gvec + k0 + 8 * c + 4); b0 = *(const f32x4*)(bvec + k0 + 8 * c); b1 = *(const f32x4*)(bvec + k0 + 8 * c + 4); }
	ds_write2_b32 v54, v2, v3 offset1:1
	ds_write2_b32 v54, v4, v5 offset0:2 offset1:3
	v_add_u32_e32 v2, 0x410, v54
	s_waitcnt vmcnt(14)
	ds_write2_b32 v2, v6, v7 offset1:1
	v_add_u32_e32 v2, 0x418, v54
	ds_write2_b32 v2, v8, v9 offset1:1
	v_add_u32_e32 v2, 0x820, v54
	s_waitcnt vmcnt(13)
	ds_write2_b32 v2, v10, v11 offset1:1
	v_add_u32_e32 v2, 0x828, v54
	ds_write2_b32 v2, v12, v13 offset1:1
	v_add_u32_e32 v2, 0xc30, v54
	s_waitcnt vmcnt(12)
	ds_write2_b32 v2, v14, v15 offset1:1
	v_add_u32_e32 v2, 0xc38, v54
	ds_write2_b32 v2, v16, v17 offset1:1
	v_add_u32_e32 v2, 0x1040, v54
	s_waitcnt vmcnt(11)
	ds_write2_b32 v2, v44, v45 offset1:1
	v_add_u32_e32 v2, 0x1048, v54
	ds_write2_b32 v2, v46, v47 offset1:1
	v_add_u32_e32 v2, 0x1450, v54
	s_waitcnt vmcnt(10)
	ds_write2_b32 v2, v56, v57 offset1:1
	v_add_u32_e32 v2, 0x1458, v54
	ds_write2_b32 v2, v58, v59 offset1:1
	v_add_u32_e32 v2, 0x1860, v54
	s_waitcnt vmcnt(9)
	ds_write2_b32 v2, v60, v61 offset1:1
	v_add_u32_e32 v2, 0x1868, v54
	ds_write2_b32 v2, v62, v63 offset1:1
	v_add_u32_e32 v2, 0x1c70, v54
	s_waitcnt vmcnt(8)
	ds_write2_b32 v2, v64, v65 offset1:1
	v_add_u32_e32 v2, 0x1c78, v54
	ds_write2_b32 v2, v66, v67 offset1:1
	v_add_u32_e32 v2, 0x2080, v54
	s_ashr_i32 s27, s26, 31
	s_and_b64 vcc, exec, s[54:55]
	s_waitcnt vmcnt(7)
	ds_write2_b32 v2, v68, v69 offset1:1
	v_add_u32_e32 v2, 0x2088, v54
	ds_write2_b32 v2, v70, v71 offset1:1
	v_add_u32_e32 v2, 0x2490, v54
	s_waitcnt vmcnt(6)
	ds_write2_b32 v2, v72, v73 offset1:1
	v_add_u32_e32 v2, 0x2498, v54
	ds_write2_b32 v2, v74, v75 offset1:1
	v_add_u32_e32 v2, 0x28a0, v54
	s_waitcnt vmcnt(5)
	ds_write2_b32 v2, v76, v77 offset1:1
	v_add_u32_e32 v2, 0x28a8, v54
	ds_write2_b32 v2, v78, v79 offset1:1
	v_add_u32_e32 v2, 0x2cb0, v54
	s_waitcnt vmcnt(4)
	ds_write2_b32 v2, v80, v81 offset1:1
	v_add_u32_e32 v2, 0x2cb8, v54
	ds_write2_b32 v2, v82, v83 offset1:1
	v_add_u32_e32 v2, 0x30c0, v54
	s_waitcnt vmcnt(3)
	ds_write2_b32 v2, v84, v85 offset1:1
	v_add_u32_e32 v2, 0x30c8, v54
	ds_write2_b32 v2, v86, v87 offset1:1
	v_add_u32_e32 v2, 0x34d0, v54
	s_waitcnt vmcnt(2)
	ds_write2_b32 v2, v88, v89 offset1:1
	v_add_u32_e32 v2, 0x34d8, v54
	ds_write2_b32 v2, v90, v91 offset1:1
	v_add_u32_e32 v2, 0x38e0, v54
	s_waitcnt vmcnt(1)
	ds_write2_b32 v2, v92, v93 offset1:1
	v_add_u32_e32 v2, 0x38e8, v54
	ds_write2_b32 v2, v94, v95 offset1:1
	v_add_u32_e32 v2, 0x3cf0, v54
	s_waitcnt vmcnt(0)
	ds_write2_b32 v2, v96, v97 offset1:1
	v_add_u32_e32 v2, 0x3cf8, v54
	ds_write2_b32 v2, v98, v99 offset1:1
	s_waitcnt lgkmcnt(0)
	s_cbranch_vccz .LBB0_68
	s_andn2_b64 vcc, exec, s[56:57]
	s_cbranch_vccnz .LBB0_69
	s_lshl_b64 s[2:3], s[26:27], 2
	v_lshl_add_u64 v[2:3], v[40:41], 0, s[2:3]
	global_load_dwordx4 v[10:13], v[2:3], off offset:16
	global_load_dwordx4 v[14:17], v[2:3], off
	v_lshl_add_u64 v[6:7], v[38:39], 0, s[2:3]
	global_load_dwordx4 v[2:5], v[6:7], off offset:16
	s_nop 0
	global_load_dwordx4 v[6:9], v[6:7], off
	s_waitcnt vmcnt(3)
	v_mov_b32_e32 v44, v11
	v_mov_b32_e32 v45, v12
	v_mov_b32_e32 v11, v13
	s_waitcnt vmcnt(2)
	v_mov_b32_e32 v46, v15
	v_mov_b32_e32 v47, v16
	v_mov_b32_e32 v15, v17
	s_branch .LBB0_70

; __device__ __forceinline__ float bflo(unsigned w) { return __uint_as_float(w << 16); }
; __device__ __forceinline__ float bfhi(unsigned w) { return __uint_as_float(w & 0xffff0000u); }
; __device__ __forceinline__ void dil_combine_load(float (&o)[16], float& rn, const bf16_t* p0, const bf16_t* p1, const bf16_t* xo, const float* lse0, const float* lse1, const float* lse2, int lane) {
;     const int h = lane >> 3, seg = lane & 7;
;     const float e0 = lse0[h], e1 = lse1[h], e2 = lse2[h], em = fmaxf(e0, fmaxf(e1, e2));
;     float w0 = __builtin_amdgcn_exp2f(e0 - em), w1 = __builtin_amdgcn_exp2f(e1 - em), w2 = __builtin_amdgcn_exp2f(e2 - em); const float wi = 1.0f / (w0 + w1 + w2); w0 *= wi; w1 *= wi; w2 *= wi;
;     const int off = h * 128 + seg * 16;
;     float ss = 0.f;
; #pragma unroll
;     for (int j = 0; j < 2; ++j) { const u32x4 a = *(const u32x4*)(p0 + off + 8 * j), bq = *(const u32x4*)(p1 + off + 8 * j), cq = *(const u32x4*)(xo + off + 8 * j);
; #pragma unroll
;         for (int e = 0; e < 4; ++e) { o[8 * j + 2 * e] = w0 * bflo(a[e]) + w1 * bflo(bq[e]) + w2 * bflo(cq[e]); o[8 * j + 2 * e + 1] = w0 * bfhi(a[e]) + w1 * bfhi(bq[e]) + w2 * bfhi(cq[e]); } }
; __global__ void __launch_bounds__(NWAVES * 64, 2) mega_fwd(Params P) {
;     ...
;           for (int m = gw; m < TOK; m += 4 * NGW) { float o[4][16], rn[4];
; #pragma unroll
;               for (int j = 0; j < 4; ++j) { const int mm = m + j * NGW; dil_combine_load(o[j], rn[j], PART0 + (size_t)mm * 1024, PART1 + (size_t)mm * 1024, XB + (size_t)mm * DM + 1024, LSE + (size_t)mm * 8, LSE + (size_t)(TOK + mm) * 8, LSE + (size_t)(2 * TOK + mm) * 8, lane); }
.LBB0_409:
	s_nop 0
	v_lshl_add_u64 v[2:3], s[76:77], 0, v[92:93]
	global_load_dword v0, v[2:3], off nt
	v_lshl_add_u64 v[2:3], s[76:77], 0, v[90:91]
	global_load_dword v4, v[2:3], off nt
	v_lshl_add_u64 v[2:3], s[76:77], 0, v[88:89]
	global_load_dword v2, v[2:3], off nt
	v_lshl_add_u64 v[12:13], s[76:77], 0, v[96:97]
	v_lshl_add_u64 v[14:15], v[12:13], 0, s[12:13]
	s_addk_i32 s2, 0x2000
	v_lshl_add_u64 v[88:89], v[88:89], 0, s[14:15]
	v_lshl_add_u64 v[90:91], v[90:91], 0, s[14:15]
	v_lshl_add_u64 v[92:93], v[92:93], 0, s[14:15]
	v_lshl_add_u64 v[96:97], v[96:97], 0, s[30:31]
	s_cmpk_gt_i32 s2, 0x5fff
	s_waitcnt vmcnt(0)
	v_max3_f32 v3, v0, v4, v2
	v_sub_f32_e32 v0, v0, v3
	v_exp_f32_e32 v219, v0
	v_sub_f32_e32 v0, v4, v3
	v_exp_f32_e32 v218, v0
	v_sub_f32_e32 v0, v2, v3
	v_exp_f32_e32 v0, v0
	v_add_f32_e32 v2, v219, v218
	v_add_f32_e32 v2, v0, v2
	v_div_scale_f32 v3, s[0:1], v2, v2, 1.0
	v_rcp_f32_e32 v4, v3
	s_nop 0
	v_fma_f32 v5, -v3, v4, 1.0
	v_fmac_f32_e32 v4, v5, v4
	v_div_scale_f32 v5, vcc, 1.0, v2, 1.0
	v_mul_f32_e32 v6, v5, v4
	v_fma_f32 v7, -v3, v6, v5
	v_fmac_f32_e32 v6, v7, v4
	v_fma_f32 v3, -v3, v6, v5
	v_div_fmas_f32 v3, v3, v4, v6
	v_lshl_add_u64 v[6:7], s[76:77], 0, v[98:99]
	v_div_fixup_f32 v220, v3, v2, 1.0
	v_add_co_u32_e32 v2, vcc, s21, v6
	v_lshl_add_u64 v[8:9], v[6:7], 0, s[6:7]
	s_nop 0
	v_addc_co_u32_e32 v3, vcc, 0, v7, vcc
	global_load_dwordx4 v[2:5], v[2:3], off nt
	s_nop 0
	global_load_dwordx4 v[58:61], v[8:9], off offset:16 nt
	v_lshl_add_u64 v[10:11], v[6:7], 0, s[8:9]
	v_add_co_u32_e32 v6, vcc, s22, v6
	v_mul_f32_e32 v178, v0, v220
	s_nop 0
	v_addc_co_u32_e32 v7, vcc, 0, v7, vcc
	global_load_dwordx4 v[6:9], v[6:7], off nt
	s_nop 0
	global_load_dwordx4 v[62:65], v[10:11], off offset:16 nt
	v_add_co_u32_e32 v10, vcc, s28, v12
	v_pk_mul_f32 v[218:219], v[218:219], v[220:221] op_sel_hi:[1,0]
	s_nop 0
	v_addc_co_u32_e32 v11, vcc, 0, v13, vcc
	global_load_dwordx4 v[54:57], v[10:11], off offset:2048 nt
	global_load_dwordx4 v[50:53], v[14:15], off offset:16 nt
	v_lshl_add_u64 v[12:13], s[76:77], 0, v[120:121]
	v_lshl_add_u64 v[14:15], v[12:13], 0, s[12:13]
	v_lshl_add_u64 v[98:99], v[98:99], 0, s[26:27]
	v_lshl_add_u64 v[120:121], v[120:121], 0, s[30:31]
	s_waitcnt vmcnt(5)
	v_lshlrev_b32_e32 v238, 16, v2
	v_and_b32_e32 v234, 0xffff0000, v2
	v_lshlrev_b32_e32 v241, 16, v3
	v_and_b32_e32 v237, 0xffff0000, v3
	v_lshl_add_u64 v[2:3], s[76:77], 0, v[116:117]
	global_load_dword v0, v[2:3], off nt
	v_lshl_add_u64 v[2:3], s[76:77], 0, v[86:87]
	v_lshlrev_b32_e32 v226, 16, v4
	v_and_b32_e32 v222, 0xffff0000, v4
	global_load_dword v4, v[2:3], off nt
	v_lshl_add_u64 v[2:3], s[76:77], 0, v[84:85]
	global_load_dword v2, v[2:3], off nt
	v_lshlrev_b32_e32 v229, 16, v5
	v_and_b32_e32 v225, 0xffff0000, v5
	s_waitcnt vmcnt(6)
	v_lshlrev_b32_e32 v240, 16, v6
	v_and_b32_e32 v236, 0xffff0000, v6
	v_lshlrev_b32_e32 v239, 16, v7
	v_and_b32_e32 v235, 0xffff0000, v7
	v_lshlrev_b32_e32 v228, 16, v8
	v_and_b32_e32 v224, 0xffff0000, v8
	v_lshlrev_b32_e32 v227, 16, v9
	v_and_b32_e32 v223, 0xffff0000, v9
	v_lshlrev_b32_e32 v217, 16, v59
	s_waitcnt vmcnt(5)
	v_lshlrev_b32_e32 v215, 16, v63
	v_and_b32_e32 v213, 0xffff0000, v59
	v_and_b32_e32 v211, 0xffff0000, v63
	v_lshlrev_b32_e32 v214, 16, v58
	v_and_b32_e32 v210, 0xffff0000, v58
	v_and_b32_e32 v184, 0xffff0000, v64
	v_lshlrev_b32_e32 v185, 16, v60
	s_waitcnt vmcnt(3)
	v_and_b32_e32 v186, 0xffff0000, v52
	v_lshlrev_b32_e32 v187, 16, v52
	v_pk_mul_f32 v[226:227], v[218:219], v[226:227] op_sel:[1,0] op_sel_hi:[0,1]
	v_pk_fma_f32 v[226:227], v[218:219], v[228:229], v[226:227]
	v_pk_mul_f32 v[222:223], v[218:219], v[222:223] op_sel:[1,0] op_sel_hi:[0,1]
	v_pk_fma_f32 v[222:223], v[218:219], v[224:225], v[222:223]
	v_lshlrev_b32_e32 v216, 16, v62
	v_pk_mul_f32 v[214:215], v[218:219], v[214:215] op_sel:[1,0] op_sel_hi:[0,1]
	v_and_b32_e32 v212, 0xffff0000, v62
	v_pk_fma_f32 v[214:215], v[218:219], v[216:217], v[214:215]
	v_pk_mul_f32 v[210:211], v[218:219], v[210:211] op_sel:[1,0] op_sel_hi:[0,1]
	v_pk_fma_f32 v[210:211], v[218:219], v[212:213], v[210:211]
	v_and_b32_e32 v52, 0xffff0000, v53
	v_lshlrev_b32_e32 v53, 16, v53
	v_lshl_add_u64 v[84:85], v[84:85], 0, s[14:15]
	v_lshl_add_u64 v[86:87], v[86:87], 0, s[14:15]
	v_lshl_add_u64 v[116:117], v[116:117], 0, s[14:15]
	s_waitcnt vmcnt(0)
	v_max3_f32 v3, v0, v4, v2
	v_sub_f32_e32 v0, v0, v3
	v_exp_f32_e32 v207, v0
	v_sub_f32_e32 v0, v4, v3
	v_exp_f32_e32 v206, v0
	v_sub_f32_e32 v0, v2, v3
	v_exp_f32_e32 v0, v0
	v_add_f32_e32 v2, v207, v206
	v_add_f32_e32 v2, v0, v2
	v_div_scale_f32 v3, s[0:1], v2, v2, 1.0
	v_rcp_f32_e32 v4, v3
	s_nop 0
	v_fma_f32 v5, -v3, v4, 1.0
	v_fmac_f32_e32 v4, v5, v4
	v_div_scale_f32 v5, vcc, 1.0, v2, 1.0
	v_mul_f32_e32 v6, v5, v4
	v_fma_f32 v7, -v3, v6, v5
	v_fmac_f32_e32 v6, v7, v4
	v_fma_f32 v3, -v3, v6, v5
	v_div_fmas_f32 v3, v3, v4, v6
	v_lshl_add_u64 v[6:7], s[76:77], 0, v[122:123]
	v_div_fixup_f32 v208, v3, v2, 1.0
	v_add_co_u32_e32 v2, vcc, s21, v6
	v_lshl_add_u64 v[8:9], v[6:7], 0, s[6:7]
	s_nop 0
	v_addc_co_u32_e32 v3, vcc, 0, v7, vcc
	global_load_dwordx4 v[2:5], v[2:3], off nt
	s_nop 0
	global_load_dwordx4 v[42:45], v[8:9], off offset:16 nt
	v_lshl_add_u64 v[10:11], v[6:7], 0, s[8:9]
	v_add_co_u32_e32 v6, vcc, s22, v6
	v_mul_f32_e32 v144, v0, v208
	s_nop 0
	v_addc_co_u32_e32 v7, vcc, 0, v7, vcc
	global_load_dwordx4 v[6:9], v[6:7], off nt
	s_nop 0
	global_load_dwordx4 v[46:49], v[10:11], off offset:16 nt
	v_add_co_u32_e32 v10, vcc, s28, v12
	v_lshl_add_u64 v[122:123], v[122:123], 0, s[26:27]
	s_nop 0
	v_addc_co_u32_e32 v11, vcc, 0, v13, vcc
	global_load_dwordx4 v[38:41], v[10:11], off offset:2048 nt
	global_load_dwordx4 v[34:37], v[14:15], off offset:16 nt
	v_lshl_add_u64 v[12:13], s[76:77], 0, v[112:113]
	v_lshl_add_u64 v[14:15], v[12:13], 0, s[12:13]
	v_lshl_add_u64 v[112:113], v[112:113], 0, s[30:31]
	s_waitcnt vmcnt(5)
; __device__ __forceinline__ float bflo(unsigned w) { return __uint_as_float(w << 16); }
; __device__ __forceinline__ float bfhi(unsigned w) { return __uint_as_float(w & 0xffff0000u); }
; __device__ __forceinline__ void dil_combine_load(float (&o)[16], float& rn, const bf16_t* p0, const bf16_t* p1, const bf16_t* xo, const float* lse0, const float* lse1, const float* lse2, int lane) {
;     const int h = lane >> 3, seg = lane & 7;
;     const float e0 = lse0[h], e1 = lse1[h], e2 = lse2[h], em = fmaxf(e0, fmaxf(e1, e2));
;     float w0 = __builtin_amdgcn_exp2f(e0 - em), w1 = __builtin_amdgcn_exp2f(e1 - em), w2 = __builtin_amdgcn_exp2f(e2 - em); const float wi = 1.0f / (w0 + w1 + w2); w0 *= wi; w1 *= wi; w2 *= wi;
;     const int off = h * 128 + seg * 16;
;     float ss = 0.f;
; #pragma unroll
;     for (int j = 0; j < 2; ++j) { const u32x4 a = *(const u32x4*)(p0 + off + 8 * j), bq = *(const u32x4*)(p1 + off + 8 * j), cq = *(const u32x4*)(xo + off + 8 * j);
; #pragma unroll
;         for (int e = 0; e < 4; ++e) { o[8 * j + 2 * e] = w0 * bflo(a[e]) + w1 * bflo(bq[e]) + w2 * bflo(cq[e]); o[8 * j + 2 * e + 1] = w0 * bfhi(a[e]) + w1 * bfhi(bq[e]) + w2 * bfhi(cq[e]); } }
; __global__ void __launch_bounds__(NWAVES * 64, 2) mega_fwd(Params P) {
;     ...
;           for (int m = gw; m < TOK; m += 4 * NGW) { float o[4][16], rn[4];
; #pragma unroll
;               for (int j = 0; j < 4; ++j) { const int mm = m + j * NGW; dil_combine_load(o[j], rn[j], PART0 + (size_t)mm * 1024, PART1 + (size_t)mm * 1024, XB + (size_t)mm * DM + 1024, LSE + (size_t)mm * 8, LSE + (size_t)(TOK + mm) * 8, LSE + (size_t)(2 * TOK + mm) * 8, lane); }
	v_lshlrev_b32_e32 v230, 16, v2
	v_and_b32_e32 v202, 0xffff0000, v2
	v_lshlrev_b32_e32 v233, 16, v3
	v_and_b32_e32 v205, 0xffff0000, v3
	v_lshl_add_u64 v[2:3], s[76:77], 0, v[108:109]
	global_load_dword v0, v[2:3], off nt
	v_lshl_add_u64 v[2:3], s[76:77], 0, v[82:83]
	v_lshlrev_b32_e32 v174, 16, v4
	v_and_b32_e32 v170, 0xffff0000, v4
	global_load_dword v4, v[2:3], off nt
	v_lshl_add_u64 v[2:3], s[76:77], 0, v[80:81]
	global_load_dword v2, v[2:3], off nt
	v_lshlrev_b32_e32 v177, 16, v5
	v_and_b32_e32 v173, 0xffff0000, v5
	s_waitcnt vmcnt(6)
	v_lshlrev_b32_e32 v232, 16, v6
	v_and_b32_e32 v204, 0xffff0000, v6
	v_lshlrev_b32_e32 v231, 16, v7
	v_and_b32_e32 v203, 0xffff0000, v7
	v_lshlrev_b32_e32 v176, 16, v8
	v_and_b32_e32 v172, 0xffff0000, v8
	v_lshlrev_b32_e32 v175, 16, v9
	v_and_b32_e32 v171, 0xffff0000, v9
	v_lshlrev_b32_e32 v166, 16, v42
	v_and_b32_e32 v162, 0xffff0000, v42
	s_waitcnt vmcnt(5)
	v_lshlrev_b32_e32 v167, 16, v47
	v_and_b32_e32 v163, 0xffff0000, v47
	v_lshlrev_b32_e32 v169, 16, v43
	v_and_b32_e32 v165, 0xffff0000, v43
	v_lshlrev_b32_e32 v168, 16, v46
	v_and_b32_e32 v164, 0xffff0000, v46
	v_lshl_add_u64 v[80:81], v[80:81], 0, s[14:15]
	v_lshl_add_u64 v[82:83], v[82:83], 0, s[14:15]
	v_lshl_add_u64 v[108:109], v[108:109], 0, s[14:15]
	s_waitcnt vmcnt(0)
	v_max3_f32 v3, v0, v4, v2
	v_sub_f32_e32 v0, v0, v3
	v_exp_f32_e32 v147, v0
	v_sub_f32_e32 v0, v4, v3
	v_exp_f32_e32 v146, v0
	v_sub_f32_e32 v0, v2, v3
	v_exp_f32_e32 v0, v0
	v_add_f32_e32 v2, v147, v146
	v_add_f32_e32 v2, v0, v2
	v_div_scale_f32 v3, s[0:1], v2, v2, 1.0
	v_rcp_f32_e32 v4, v3
	s_nop 0
	v_fma_f32 v5, -v3, v4, 1.0
	v_fmac_f32_e32 v4, v5, v4
	v_div_scale_f32 v5, vcc, 1.0, v2, 1.0
	v_mul_f32_e32 v6, v5, v4
	v_fma_f32 v7, -v3, v6, v5
	v_fmac_f32_e32 v6, v7, v4
	v_fma_f32 v3, -v3, v6, v5
	v_div_fmas_f32 v3, v3, v4, v6
	v_lshl_add_u64 v[6:7], s[76:77], 0, v[114:115]
	v_div_fixup_f32 v148, v3, v2, 1.0
	v_add_co_u32_e32 v2, vcc, s21, v6
	v_lshl_add_u64 v[8:9], v[6:7], 0, s[6:7]
	s_nop 0
	v_addc_co_u32_e32 v3, vcc, 0, v7, vcc
	global_load_dwordx4 v[2:5], v[2:3], off nt
	s_nop 0
	global_load_dwordx4 v[26:29], v[8:9], off offset:16 nt
	v_lshl_add_u64 v[10:11], v[6:7], 0, s[8:9]
	v_add_co_u32_e32 v6, vcc, s22, v6
	v_mul_f32_e32 v42, v0, v148
	s_nop 0
	v_addc_co_u32_e32 v7, vcc, 0, v7, vcc
	global_load_dwordx4 v[6:9], v[6:7], off nt
	s_nop 0
	global_load_dwordx4 v[30:33], v[10:11], off offset:16 nt
	v_add_co_u32_e32 v10, vcc, s28, v12
	v_lshl_add_u64 v[114:115], v[114:115], 0, s[26:27]
	s_nop 0
	v_addc_co_u32_e32 v11, vcc, 0, v13, vcc
	global_load_dwordx4 v[22:25], v[10:11], off offset:2048 nt
	global_load_dwordx4 v[18:21], v[14:15], off offset:16 nt
	v_lshl_add_u64 v[14:15], s[76:77], 0, v[104:105]
	v_lshl_add_u64 v[104:105], v[104:105], 0, s[30:31]
	s_waitcnt vmcnt(5)
	v_lshlrev_b32_e32 v198, 16, v2
	v_and_b32_e32 v150, 0xffff0000, v2
	v_lshlrev_b32_e32 v201, 16, v3
	v_and_b32_e32 v153, 0xffff0000, v3
	v_lshl_add_u64 v[2:3], s[76:77], 0, v[100:101]
	global_load_dword v0, v[2:3], off nt
	v_lshl_add_u64 v[2:3], s[76:77], 0, v[78:79]
	v_lshlrev_b32_e32 v140, 16, v4
	v_and_b32_e32 v136, 0xffff0000, v4
	global_load_dword v4, v[2:3], off nt
	v_lshl_add_u64 v[2:3], s[76:77], 0, v[76:77]
	global_load_dword v2, v[2:3], off nt
	v_lshlrev_b32_e32 v143, 16, v5
	v_and_b32_e32 v139, 0xffff0000, v5
	s_waitcnt vmcnt(6)
	v_lshlrev_b32_e32 v200, 16, v6
	v_and_b32_e32 v152, 0xffff0000, v6
	v_lshlrev_b32_e32 v199, 16, v7
	v_and_b32_e32 v151, 0xffff0000, v7
	v_lshlrev_b32_e32 v142, 16, v8
	v_and_b32_e32 v138, 0xffff0000, v8
	v_lshlrev_b32_e32 v141, 16, v9
	v_and_b32_e32 v137, 0xffff0000, v9
	v_lshlrev_b32_e32 v132, 16, v26
	v_and_b32_e32 v128, 0xffff0000, v26
	v_lshlrev_b32_e32 v135, 16, v27
	s_waitcnt vmcnt(5)
	v_lshlrev_b32_e32 v133, 16, v31
	v_and_b32_e32 v131, 0xffff0000, v27
	v_and_b32_e32 v129, 0xffff0000, v31
	v_lshl_add_u64 v[26:27], v[14:15], 0, s[12:13]
	v_lshlrev_b32_e32 v134, 16, v30
	v_and_b32_e32 v130, 0xffff0000, v30
	v_lshl_add_u64 v[76:77], v[76:77], 0, s[14:15]
	v_lshl_add_u64 v[78:79], v[78:79], 0, s[14:15]
	v_lshl_add_u64 v[100:101], v[100:101], 0, s[14:15]
	s_waitcnt vmcnt(0)
	v_max3_f32 v3, v0, v4, v2
	v_sub_f32_e32 v0, v0, v3
	v_exp_f32_e32 v125, v0
	v_sub_f32_e32 v0, v4, v3
	v_exp_f32_e32 v124, v0
	v_sub_f32_e32 v0, v2, v3
	v_exp_f32_e32 v0, v0
	v_add_f32_e32 v2, v125, v124
	v_add_f32_e32 v2, v0, v2
	v_div_scale_f32 v3, s[0:1], v2, v2, 1.0
	v_rcp_f32_e32 v4, v3
	s_nop 0
	v_fma_f32 v5, -v3, v4, 1.0
	v_fmac_f32_e32 v4, v5, v4
	v_div_scale_f32 v5, vcc, 1.0, v2, 1.0
	v_mul_f32_e32 v6, v5, v4
	v_fma_f32 v7, -v3, v6, v5
	v_fmac_f32_e32 v6, v7, v4
	v_fma_f32 v3, -v3, v6, v5
	v_div_fmas_f32 v3, v3, v4, v6
	v_div_fixup_f32 v126, v3, v2, 1.0
	v_lshl_add_u64 v[2:3], s[76:77], 0, v[106:107]
	v_add_co_u32_e32 v6, vcc, s21, v2
	v_lshl_add_u64 v[4:5], v[2:3], 0, s[6:7]
	s_nop 0
	v_addc_co_u32_e32 v7, vcc, 0, v3, vcc
	v_lshl_add_u64 v[10:11], v[2:3], 0, s[8:9]
	v_add_co_u32_e32 v2, vcc, s22, v2
	global_load_dwordx4 v[66:69], v[6:7], off nt
	s_nop 0
	global_load_dwordx4 v[6:9], v[4:5], off offset:16 nt
	v_addc_co_u32_e32 v3, vcc, 0, v3, vcc
	global_load_dwordx4 v[70:73], v[2:3], off nt
	s_nop 0
	global_load_dwordx4 v[10:13], v[10:11], off offset:16 nt
	v_add_co_u32_e32 v2, vcc, s28, v14
	v_mul_f32_e32 v0, v0, v126
	s_nop 0
	v_addc_co_u32_e32 v3, vcc, 0, v15, vcc
	global_load_dwordx4 v[14:17], v[2:3], off offset:2048 nt
	s_nop 0
	global_load_dwordx4 v[2:5], v[26:27], off offset:16 nt
	v_lshl_add_u64 v[106:107], v[106:107], 0, s[26:27]
	s_waitcnt vmcnt(5)
	v_lshlrev_b32_e32 v158, 16, v66
	v_and_b32_e32 v154, 0xffff0000, v66
	v_lshlrev_b32_e32 v59, 16, v69
	s_waitcnt vmcnt(3)
; __device__ __forceinline__ float sx(float v, int mask, int lane) { return __int_as_float(__builtin_amdgcn_ds_bpermute((lane ^ mask) << 2, __float_as_int(v))); }
; __device__ __forceinline__ float bflo(unsigned w) { return __uint_as_float(w << 16); }
; __device__ __forceinline__ float bfhi(unsigned w) { return __uint_as_float(w & 0xffff0000u); }
; __device__ __forceinline__ unsigned pk2(float lo, float hi) { return f2bf(lo) | (f2bf(hi) << 16); }
; __device__ __forceinline__ void dil_combine_load(float (&o)[16], float& rn, const bf16_t* p0, const bf16_t* p1, const bf16_t* xo, const float* lse0, const float* lse1, const float* lse2, int lane) {
;     ...
;     for (int j = 0; j < 2; ++j) { const u32x4 a = *(const u32x4*)(p0 + off + 8 * j), bq = *(const u32x4*)(p1 + off + 8 * j), cq = *(const u32x4*)(xo + off + 8 * j);
; #pragma unroll
;         for (int e = 0; e < 4; ++e) { o[8 * j + 2 * e] = w0 * bflo(a[e]) + w1 * bflo(bq[e]) + w2 * bflo(cq[e]); o[8 * j + 2 * e + 1] = w0 * bfhi(a[e]) + w1 * bfhi(bq[e]) + w2 * bfhi(cq[e]); } }
; #pragma unroll
;     for (int d = 0; d < 16; ++d) ss += o[d] * o[d];
;     ss += sx(ss, 1, lane); ss += sx(ss, 2, lane); ss += sx(ss, 4, lane);
;     rn = 1.0f / sqrtf(ss * (1.f / 128.f) + RMS_EPS);
; }
; __device__ __forceinline__ void dil_combine_store(const float (&o)[16], float rn, bf16_t* xo, const float* g_dil, int lane) {
;     const int h = lane >> 3, seg = lane & 7; const int off = h * 128 + seg * 16;
; #pragma unroll
;     for (int j = 0; j < 2; ++j) { u32x4 w;
; #pragma unroll
;         for (int e = 0; e < 4; ++e) w[e] = pk2(o[8 * j + 2 * e] * rn * g_dil[seg * 16 + 8 * j + 2 * e], o[8 * j + 2 * e + 1] * rn * g_dil[seg * 16 + 8 * j + 2 * e + 1]);
;         *(u32x4*)(xo + off + 8 * j) = w; }
	v_lshlrev_b32_e32 v160, 16, v70
	v_and_b32_e32 v156, 0xffff0000, v70
	v_and_b32_e32 v31, 0xffff0000, v69
	s_waitcnt vmcnt(2)
	v_lshlrev_b32_e32 v70, 16, v10
	v_and_b32_e32 v66, 0xffff0000, v10
	v_lshlrev_b32_e32 v69, 16, v11
	v_and_b32_e32 v63, 0xffff0000, v11
	v_pk_mul_f32 v[10:11], v[218:219], v[238:239] op_sel:[1,0] op_sel_hi:[0,1]
	v_lshlrev_b32_e32 v58, 16, v72
	v_and_b32_e32 v30, 0xffff0000, v72
	v_lshlrev_b32_e32 v47, 16, v73
	v_and_b32_e32 v27, 0xffff0000, v73
	v_pk_fma_f32 v[10:11], v[218:219], v[240:241], v[10:11]
	v_lshlrev_b32_e32 v73, 16, v55
	v_lshlrev_b32_e32 v72, 16, v54
	v_pk_fma_f32 v[10:11], v[178:179], v[72:73], v[10:11] op_sel_hi:[0,1,1]
	v_pk_mul_f32 v[72:73], v[218:219], v[234:235] op_sel:[1,0] op_sel_hi:[0,1]
	v_pk_fma_f32 v[72:73], v[218:219], v[236:237], v[72:73]
	v_and_b32_e32 v55, 0xffff0000, v55
	v_and_b32_e32 v54, 0xffff0000, v54
	v_pk_fma_f32 v[54:55], v[178:179], v[54:55], v[72:73] op_sel_hi:[0,1,1]
	v_and_b32_e32 v72, 0xffff0000, v60
	v_lshlrev_b32_e32 v73, 16, v64
	v_pk_mul_f32 v[72:73], v[218:219], v[72:73] op_sel:[1,0] op_sel_hi:[0,1]
	v_pk_fma_f32 v[72:73], v[218:219], v[184:185], v[72:73]
	v_and_b32_e32 v184, 0xffff0000, v61
	v_lshlrev_b32_e32 v185, 16, v65
	v_pk_fma_f32 v[72:73], v[178:179], v[186:187], v[72:73] op_sel_hi:[0,1,1]
	v_and_b32_e32 v60, 0xffff0000, v65
	v_pk_mul_f32 v[64:65], v[218:219], v[184:185] op_sel:[1,0] op_sel_hi:[0,1]
	ds_read_b128 v[184:187], v74 offset:16
	ds_read_b128 v[234:237], v74
	v_pk_mul_f32 v[194:195], v[10:11], v[10:11]
	v_pk_mul_f32 v[196:197], v[54:55], v[54:55]
	v_lshlrev_b32_e32 v61, 16, v61
	v_pk_fma_f32 v[60:61], v[218:219], v[60:61], v[64:65]
	v_add_f32_e32 v43, v194, v196
	v_add_f32_e32 v43, v195, v43
	v_add_f32_e32 v43, v197, v43
	v_pk_mul_f32 v[220:221], v[72:73], v[72:73]
	v_pk_fma_f32 v[60:61], v[178:179], v[52:53], v[60:61] op_sel_hi:[0,1,1]
	v_pk_mul_f32 v[52:53], v[60:61], v[60:61]
	v_lshlrev_b32_e32 v161, 16, v67
	v_lshlrev_b32_e32 v159, 16, v71
	v_and_b32_e32 v157, 0xffff0000, v67
	v_and_b32_e32 v155, 0xffff0000, v71
	v_lshlrev_b32_e32 v46, 16, v68
	v_and_b32_e32 v26, 0xffff0000, v68
	v_lshlrev_b32_e32 v68, 16, v6
	v_and_b32_e32 v62, 0xffff0000, v6
	v_lshlrev_b32_e32 v71, 16, v7
	v_and_b32_e32 v67, 0xffff0000, v7
	v_lshl_add_u64 v[6:7], s[76:77], 0, v[94:95]
	v_lshl_add_u64 v[94:95], v[94:95], 0, s[30:31]
	s_waitcnt vmcnt(0) lgkmcnt(0)
	v_mov_b32_e32 v228, v184
	s_waitcnt lgkmcnt(0)
	v_mov_b32_e32 v64, v234
	v_mov_b32_e32 v65, v236
	v_mov_b32_e32 v236, v235
	v_lshlrev_b32_e32 v235, 16, v57
	v_lshlrev_b32_e32 v234, 16, v56
	v_and_b32_e32 v57, 0xffff0000, v57
	v_and_b32_e32 v56, 0xffff0000, v56
	v_pk_fma_f32 v[226:227], v[178:179], v[234:235], v[226:227] op_sel_hi:[0,1,1]
	v_pk_fma_f32 v[56:57], v[178:179], v[56:57], v[222:223] op_sel_hi:[0,1,1]
	v_pk_mul_f32 v[222:223], v[226:227], v[226:227]
	v_pk_mul_f32 v[224:225], v[56:57], v[56:57]
	v_add_f32_e32 v43, v222, v43
	v_mov_b32_e32 v229, v186
	v_mov_b32_e32 v186, v185
	v_lshlrev_b32_e32 v185, 16, v51
	v_lshlrev_b32_e32 v184, 16, v50
	v_add_f32_e32 v43, v224, v43
	v_and_b32_e32 v51, 0xffff0000, v51
	v_and_b32_e32 v50, 0xffff0000, v50
	v_pk_fma_f32 v[184:185], v[178:179], v[184:185], v[214:215] op_sel_hi:[0,1,1]
	v_add_f32_e32 v43, v223, v43
	v_pk_fma_f32 v[210:211], v[178:179], v[50:51], v[210:211] op_sel_hi:[0,1,1]
	v_pk_mul_f32 v[50:51], v[184:185], v[184:185]
	v_add_f32_e32 v43, v225, v43
	v_pk_mul_f32 v[212:213], v[210:211], v[210:211]
	v_add_f32_e32 v43, v43, v50
	v_add_f32_e32 v43, v212, v43
	v_add_f32_e32 v43, v51, v43
	v_add_f32_e32 v43, v213, v43
	v_add_f32_e32 v43, v221, v43
	v_add_f32_e32 v43, v220, v43
	v_add_f32_e32 v43, v53, v43
	v_add_f32_e32 v43, v52, v43
	ds_bpermute_b32 v50, v127, v43
	s_waitcnt lgkmcnt(0)
	v_add_f32_e32 v43, v43, v50
	ds_bpermute_b32 v50, v145, v43
	s_waitcnt lgkmcnt(0)
	v_add_f32_e32 v43, v43, v50
	ds_bpermute_b32 v50, v149, v43
	s_waitcnt lgkmcnt(0)
	v_add_f32_e32 v43, v43, v50
	v_fmamk_f32 v43, v43, 0x3c000000, v244
	v_cmp_gt_f32_e32 vcc, s3, v43
	v_mul_f32_e32 v50, 0x4f800000, v43
	s_nop 0
	v_cndmask_b32_e32 v43, v43, v50, vcc
	v_sqrt_f32_e32 v50, v43
	s_nop 0
	v_add_u32_e32 v51, -1, v50
	v_fma_f32 v52, -v51, v50, v43
	v_cmp_ge_f32_e64 s[4:5], 0, v52
	v_add_u32_e32 v52, 1, v50
	s_nop 0
	v_cndmask_b32_e64 v51, v50, v51, s[4:5]
	v_fma_f32 v50, -v52, v50, v43
	v_cmp_lt_f32_e64 s[4:5], 0, v50
	s_nop 1
	v_cndmask_b32_e64 v50, v51, v52, s[4:5]
	v_mul_f32_e32 v51, 0x37800000, v50
	v_cndmask_b32_e32 v50, v50, v51, vcc
	v_cmp_class_f32_e32 vcc, v43, v245
	s_nop 1
	v_cndmask_b32_e32 v43, v50, v43, vcc
	v_div_scale_f32 v50, s[0:1], v43, v43, 1.0
	v_rcp_f32_e32 v51, v50
	s_nop 0
	v_fma_f32 v52, -v50, v51, 1.0
	v_fmac_f32_e32 v51, v52, v51
	v_div_scale_f32 v52, vcc, 1.0, v43, 1.0
	v_mul_f32_e32 v53, v52, v51
	v_fma_f32 v178, -v50, v53, v52
	v_fmac_f32_e32 v53, v178, v51
	v_fma_f32 v50, -v50, v53, v52
	v_div_fmas_f32 v50, v50, v51, v53
	v_div_fixup_f32 v178, v50, v43, 1.0
	v_pk_mul_f32 v[50:51], v[178:179], v[54:55] op_sel_hi:[0,1]
	v_pk_mul_f32 v[54:55], v[178:179], v[56:57] op_sel_hi:[0,1]
	v_pk_mul_f32 v[10:11], v[178:179], v[10:11] op_sel_hi:[0,1]
	v_pk_mul_f32 v[50:51], v[50:51], v[236:237]
	v_pk_mul_f32 v[52:53], v[178:179], v[226:227] op_sel_hi:[0,1]
	v_pk_mul_f32 v[54:55], v[54:55], v[186:187]
	v_pk_mul_f32 v[10:11], v[10:11], v[64:65]
	v_pk_mul_f32 v[52:53], v[52:53], v[228:229]
	v_bfe_u32 v43, v55, 16, 1
	v_bfe_u32 v56, v54, 16, 1
	v_bfe_u32 v57, v51, 16, 1
	v_bfe_u32 v64, v50, 16, 1
	v_add3_u32 v50, v50, v64, s11
	v_add3_u32 v51, v51, v57, s11
	v_add3_u32 v54, v54, v56, s11
	v_add3_u32 v43, v55, v43, s11
	v_bfe_u32 v55, v10, 16, 1
	v_bfe_u32 v56, v11, 16, 1
	v_bfe_u32 v57, v52, 16, 1
	v_bfe_u32 v64, v53, 16, 1
	v_add3_u32 v53, v53, v64, s11
	v_add3_u32 v52, v52, v57, s11
	v_add3_u32 v11, v11, v56, s11
	v_add3_u32 v10, v10, v55, s11
	v_lshrrev_b32_e32 v10, 16, v10
	v_lshrrev_b32_e32 v11, 16, v11
	v_lshrrev_b32_e32 v52, 16, v52
	v_lshrrev_b32_e32 v53, 16, v53
	v_add_co_u32_e32 v6, vcc, s28, v6
	v_and_or_b32 v53, v43, s23, v53
	v_and_or_b32 v52, v54, s23, v52
	v_and_or_b32 v51, v51, s23, v11
	v_and_or_b32 v50, v50, s23, v10
	v_addc_co_u32_e32 v7, vcc, 0, v7, vcc
	global_store_dwordx4 v[6:7], v[50:53], off offset:2048
	ds_read_b128 v[50:53], v74 offset:48
	s_nop 0
	ds_read_b128 v[54:57], v74 offset:32
	v_pk_mul_f32 v[10:11], v[178:179], v[184:185] op_sel_hi:[0,1]
	s_waitcnt lgkmcnt(0)
; __device__ __forceinline__ float sx(float v, int mask, int lane) { return __int_as_float(__builtin_amdgcn_ds_bpermute((lane ^ mask) << 2, __float_as_int(v))); }
; __device__ __forceinline__ float bflo(unsigned w) { return __uint_as_float(w << 16); }
; __device__ __forceinline__ float bfhi(unsigned w) { return __uint_as_float(w & 0xffff0000u); }
; __device__ __forceinline__ unsigned pk2(float lo, float hi) { return f2bf(lo) | (f2bf(hi) << 16); }
; __device__ __forceinline__ void dil_combine_load(float (&o)[16], float& rn, const bf16_t* p0, const bf16_t* p1, const bf16_t* xo, const float* lse0, const float* lse1, const float* lse2, int lane) {
;     ...
;     for (int j = 0; j < 2; ++j) { const u32x4 a = *(const u32x4*)(p0 + off + 8 * j), bq = *(const u32x4*)(p1 + off + 8 * j), cq = *(const u32x4*)(xo + off + 8 * j);
; #pragma unroll
;         for (int e = 0; e < 4; ++e) { o[8 * j + 2 * e] = w0 * bflo(a[e]) + w1 * bflo(bq[e]) + w2 * bflo(cq[e]); o[8 * j + 2 * e + 1] = w0 * bfhi(a[e]) + w1 * bfhi(bq[e]) + w2 * bfhi(cq[e]); } }
; #pragma unroll
;     for (int d = 0; d < 16; ++d) ss += o[d] * o[d];
;     ss += sx(ss, 1, lane); ss += sx(ss, 2, lane); ss += sx(ss, 4, lane);
;     rn = 1.0f / sqrtf(ss * (1.f / 128.f) + RMS_EPS);
; }
; __device__ __forceinline__ void dil_combine_store(const float (&o)[16], float rn, bf16_t* xo, const float* g_dil, int lane) {
;     const int h = lane >> 3, seg = lane & 7; const int off = h * 128 + seg * 16;
; #pragma unroll
;     for (int j = 0; j < 2; ++j) { u32x4 w;
; #pragma unroll
;         for (int e = 0; e < 4; ++e) w[e] = pk2(o[8 * j + 2 * e] * rn * g_dil[seg * 16 + 8 * j + 2 * e], o[8 * j + 2 * e + 1] * rn * g_dil[seg * 16 + 8 * j + 2 * e + 1]);
;         *(u32x4*)(xo + off + 8 * j) = w; }
	v_mov_b32_e32 v64, v54
	v_mov_b32_e32 v65, v56
	v_pk_mul_f32 v[10:11], v[10:11], v[64:65]
	v_pk_mul_f32 v[64:65], v[178:179], v[210:211] op_sel_hi:[0,1]
	v_mov_b32_e32 v56, v55
	v_pk_mul_f32 v[54:55], v[64:65], v[56:57]
	v_mov_b32_e32 v56, v73
	v_mov_b32_e32 v73, v60
	v_mov_b32_e32 v57, v61
	v_mov_b32_e32 v65, v52
	v_pk_mul_f32 v[60:61], v[178:179], v[72:73] op_sel_hi:[0,1]
	v_mov_b32_e32 v52, v51
	v_pk_mul_f32 v[56:57], v[178:179], v[56:57] op_sel_hi:[0,1]
	v_mov_b32_e32 v64, v50
	v_pk_mul_f32 v[50:51], v[60:61], v[52:53]
	v_pk_mul_f32 v[56:57], v[56:57], v[64:65]
	v_bfe_u32 v43, v51, 16, 1
	v_bfe_u32 v52, v50, 16, 1
	v_bfe_u32 v53, v55, 16, 1
	v_bfe_u32 v60, v54, 16, 1
	v_add3_u32 v54, v54, v60, s11
	v_add3_u32 v55, v55, v53, s11
	v_add3_u32 v50, v50, v52, s11
	v_add3_u32 v43, v51, v43, s11
	v_bfe_u32 v51, v10, 16, 1
	v_bfe_u32 v52, v11, 16, 1
	v_bfe_u32 v53, v56, 16, 1
	v_bfe_u32 v60, v57, 16, 1
	v_add3_u32 v57, v57, v60, s11
	v_add3_u32 v53, v56, v53, s11
	v_add3_u32 v11, v11, v52, s11
	v_add3_u32 v10, v10, v51, s11
	v_lshrrev_b32_e32 v10, 16, v10
	v_lshrrev_b32_e32 v11, 16, v11
	v_lshrrev_b32_e32 v51, 16, v53
	v_lshrrev_b32_e32 v52, 16, v57
	v_and_or_b32 v53, v43, s23, v52
	v_and_or_b32 v52, v50, s23, v51
	v_and_or_b32 v51, v55, s23, v11
	v_and_or_b32 v50, v54, s23, v10
	v_pk_mul_f32 v[10:11], v[206:207], v[208:209] op_sel_hi:[1,0]
	global_store_dwordx4 v[6:7], v[50:53], off offset:2064
	v_and_b32_e32 v56, 0xffff0000, v44
	v_lshlrev_b32_e32 v57, 16, v48
	v_pk_mul_f32 v[50:51], v[10:11], v[230:231] op_sel:[1,0] op_sel_hi:[0,1]
	v_pk_fma_f32 v[50:51], v[10:11], v[232:233], v[50:51]
	v_lshlrev_b32_e32 v53, 16, v39
	v_lshlrev_b32_e32 v52, 16, v38
	v_pk_fma_f32 v[50:51], v[144:145], v[52:53], v[50:51] op_sel_hi:[0,1,1]
	v_pk_mul_f32 v[52:53], v[10:11], v[202:203] op_sel:[1,0] op_sel_hi:[0,1]
	v_pk_fma_f32 v[52:53], v[10:11], v[204:205], v[52:53]
	ds_read_b128 v[184:187], v74 offset:16
	ds_read_b128 v[202:205], v74
	v_and_b32_e32 v60, 0xffff0000, v48
	v_lshlrev_b32_e32 v61, 16, v44
	v_pk_mul_f32 v[56:57], v[10:11], v[56:57] op_sel:[1,0] op_sel_hi:[0,1]
	v_and_b32_e32 v39, 0xffff0000, v39
	v_and_b32_e32 v38, 0xffff0000, v38
	v_and_b32_e32 v64, 0xffff0000, v36
	v_lshlrev_b32_e32 v65, 16, v36
	v_pk_fma_f32 v[56:57], v[10:11], v[60:61], v[56:57]
	v_pk_fma_f32 v[38:39], v[144:145], v[38:39], v[52:53] op_sel_hi:[0,1,1]
	v_pk_fma_f32 v[56:57], v[144:145], v[64:65], v[56:57] op_sel_hi:[0,1,1]
	v_and_b32_e32 v64, 0xffff0000, v45
	v_lshlrev_b32_e32 v65, 16, v49
	v_pk_mul_f32 v[72:73], v[10:11], v[174:175] op_sel:[1,0] op_sel_hi:[0,1]
	v_pk_mul_f32 v[52:53], v[50:51], v[50:51]
	v_pk_mul_f32 v[54:55], v[38:39], v[38:39]
	v_and_b32_e32 v44, 0xffff0000, v49
	v_pk_mul_f32 v[48:49], v[10:11], v[64:65] op_sel:[1,0] op_sel_hi:[0,1]
	v_lshlrev_b32_e32 v65, 16, v41
	v_lshlrev_b32_e32 v64, 16, v40
	v_pk_fma_f32 v[72:73], v[10:11], v[176:177], v[72:73]
	v_add_f32_e32 v43, v52, v54
	v_pk_fma_f32 v[64:65], v[144:145], v[64:65], v[72:73] op_sel_hi:[0,1,1]
	v_pk_mul_f32 v[72:73], v[10:11], v[170:171] op_sel:[1,0] op_sel_hi:[0,1]
	v_and_b32_e32 v41, 0xffff0000, v41
	v_and_b32_e32 v40, 0xffff0000, v40
	v_pk_fma_f32 v[72:73], v[10:11], v[172:173], v[72:73]
	v_add_f32_e32 v43, v53, v43
	v_pk_fma_f32 v[40:41], v[144:145], v[40:41], v[72:73] op_sel_hi:[0,1,1]
	v_pk_mul_f32 v[72:73], v[64:65], v[64:65]
	v_add_f32_e32 v43, v55, v43
	v_pk_mul_f32 v[170:171], v[40:41], v[40:41]
	v_pk_mul_f32 v[166:167], v[10:11], v[166:167] op_sel:[1,0] op_sel_hi:[0,1]
	v_add_f32_e32 v43, v72, v43
	v_lshlrev_b32_e32 v45, 16, v45
	v_lshlrev_b32_e32 v175, 16, v35
	v_lshlrev_b32_e32 v174, 16, v34
	v_pk_fma_f32 v[166:167], v[10:11], v[168:169], v[166:167]
	v_pk_mul_f32 v[162:163], v[10:11], v[162:163] op_sel:[1,0] op_sel_hi:[0,1]
	v_add_f32_e32 v43, v170, v43
	v_pk_fma_f32 v[44:45], v[10:11], v[44:45], v[48:49]
	v_and_b32_e32 v35, 0xffff0000, v35
	v_and_b32_e32 v34, 0xffff0000, v34
	v_pk_fma_f32 v[166:167], v[144:145], v[174:175], v[166:167] op_sel_hi:[0,1,1]
	v_pk_fma_f32 v[10:11], v[10:11], v[164:165], v[162:163]
	v_add_f32_e32 v43, v73, v43
	v_pk_fma_f32 v[10:11], v[144:145], v[34:35], v[10:11] op_sel_hi:[0,1,1]
	v_pk_mul_f32 v[34:35], v[166:167], v[166:167]
	v_add_f32_e32 v43, v171, v43
	v_pk_mul_f32 v[162:163], v[10:11], v[10:11]
	v_add_f32_e32 v34, v43, v34
	v_add_f32_e32 v34, v162, v34
	v_add_f32_e32 v34, v35, v34
	v_pk_mul_f32 v[60:61], v[56:57], v[56:57]
	v_and_b32_e32 v36, 0xffff0000, v37
	v_lshlrev_b32_e32 v37, 16, v37
	v_add_f32_e32 v34, v163, v34
	v_pk_fma_f32 v[44:45], v[144:145], v[36:37], v[44:45] op_sel_hi:[0,1,1]
	v_add_f32_e32 v34, v61, v34
	v_pk_mul_f32 v[36:37], v[44:45], v[44:45]
	v_add_f32_e32 v34, v60, v34
	v_add_f32_e32 v34, v37, v34
	v_add_f32_e32 v34, v36, v34
	ds_bpermute_b32 v35, v127, v34
	v_lshl_add_u64 v[6:7], s[76:77], 0, v[118:119]
	v_lshl_add_u64 v[118:119], v[118:119], 0, s[30:31]
	s_waitcnt lgkmcnt(0)
	v_add_f32_e32 v34, v34, v35
	ds_bpermute_b32 v35, v145, v34
	s_waitcnt lgkmcnt(0)
	v_add_f32_e32 v34, v34, v35
	ds_bpermute_b32 v35, v149, v34
	s_waitcnt lgkmcnt(0)
	v_mov_b32_e32 v173, v186
	s_waitcnt lgkmcnt(0)
	v_add_f32_e32 v34, v34, v35
	v_fmamk_f32 v34, v34, 0x3c000000, v244
	v_cmp_gt_f32_e32 vcc, s3, v34
	v_mul_f32_e32 v35, 0x4f800000, v34
	s_waitcnt lgkmcnt(0)
; __device__ __forceinline__ float sx(float v, int mask, int lane) { return __int_as_float(__builtin_amdgcn_ds_bpermute((lane ^ mask) << 2, __float_as_int(v))); }
; __device__ __forceinline__ float bflo(unsigned w) { return __uint_as_float(w << 16); }
; __device__ __forceinline__ float bfhi(unsigned w) { return __uint_as_float(w & 0xffff0000u); }
; __device__ __forceinline__ unsigned pk2(float lo, float hi) { return f2bf(lo) | (f2bf(hi) << 16); }
; __device__ __forceinline__ void dil_combine_load(float (&o)[16], float& rn, const bf16_t* p0, const bf16_t* p1, const bf16_t* xo, const float* lse0, const float* lse1, const float* lse2, int lane) {
;     ...
;     for (int j = 0; j < 2; ++j) { const u32x4 a = *(const u32x4*)(p0 + off + 8 * j), bq = *(const u32x4*)(p1 + off + 8 * j), cq = *(const u32x4*)(xo + off + 8 * j);
; #pragma unroll
;         for (int e = 0; e < 4; ++e) { o[8 * j + 2 * e] = w0 * bflo(a[e]) + w1 * bflo(bq[e]) + w2 * bflo(cq[e]); o[8 * j + 2 * e + 1] = w0 * bfhi(a[e]) + w1 * bfhi(bq[e]) + w2 * bfhi(cq[e]); } }
; #pragma unroll
;     for (int d = 0; d < 16; ++d) ss += o[d] * o[d];
;     ss += sx(ss, 1, lane); ss += sx(ss, 2, lane); ss += sx(ss, 4, lane);
;     rn = 1.0f / sqrtf(ss * (1.f / 128.f) + RMS_EPS);
; }
; __device__ __forceinline__ void dil_combine_store(const float (&o)[16], float rn, bf16_t* xo, const float* g_dil, int lane) {
;     const int h = lane >> 3, seg = lane & 7; const int off = h * 128 + seg * 16;
; #pragma unroll
;     for (int j = 0; j < 2; ++j) { u32x4 w;
; #pragma unroll
;         for (int e = 0; e < 4; ++e) w[e] = pk2(o[8 * j + 2 * e] * rn * g_dil[seg * 16 + 8 * j + 2 * e], o[8 * j + 2 * e + 1] * rn * g_dil[seg * 16 + 8 * j + 2 * e + 1]);
;         *(u32x4*)(xo + off + 8 * j) = w; }
	v_mov_b32_e32 v49, v204
	v_cndmask_b32_e32 v34, v34, v35, vcc
	v_sqrt_f32_e32 v35, v34
	v_mov_b32_e32 v204, v203
	v_mov_b32_e32 v186, v185
	v_mov_b32_e32 v48, v202
	v_add_u32_e32 v36, -1, v35
	v_fma_f32 v37, -v36, v35, v34
	v_cmp_ge_f32_e64 s[4:5], 0, v37
	v_add_u32_e32 v37, 1, v35
	v_mov_b32_e32 v172, v184
	v_cndmask_b32_e64 v36, v35, v36, s[4:5]
	v_fma_f32 v35, -v37, v35, v34
	v_cmp_lt_f32_e64 s[4:5], 0, v35
	s_nop 1
	v_cndmask_b32_e64 v35, v36, v37, s[4:5]
	v_mul_f32_e32 v36, 0x37800000, v35
	v_cndmask_b32_e32 v35, v35, v36, vcc
	v_cmp_class_f32_e32 vcc, v34, v245
	s_nop 1
	v_cndmask_b32_e32 v34, v35, v34, vcc
	v_div_scale_f32 v35, s[0:1], v34, v34, 1.0
	v_rcp_f32_e32 v36, v35
	s_nop 0
	v_fma_f32 v37, -v35, v36, 1.0
	v_fmac_f32_e32 v36, v37, v36
	v_div_scale_f32 v37, vcc, 1.0, v34, 1.0
	v_mul_f32_e32 v43, v37, v36
	v_fma_f32 v52, -v35, v43, v37
	v_fmac_f32_e32 v43, v52, v36
	v_fma_f32 v35, -v35, v43, v37
	v_div_fmas_f32 v35, v35, v36, v43
	v_div_fixup_f32 v52, v35, v34, 1.0
	v_pk_mul_f32 v[36:37], v[52:53], v[38:39] op_sel_hi:[0,1]
	v_pk_mul_f32 v[40:41], v[52:53], v[40:41] op_sel_hi:[0,1]
	v_pk_mul_f32 v[34:35], v[52:53], v[50:51] op_sel_hi:[0,1]
	v_pk_mul_f32 v[36:37], v[36:37], v[204:205]
	v_pk_mul_f32 v[38:39], v[52:53], v[64:65] op_sel_hi:[0,1]
	v_pk_mul_f32 v[40:41], v[40:41], v[186:187]
	v_pk_mul_f32 v[34:35], v[34:35], v[48:49]
	v_pk_mul_f32 v[38:39], v[38:39], v[172:173]
	v_bfe_u32 v43, v41, 16, 1
	v_bfe_u32 v48, v40, 16, 1
	v_bfe_u32 v49, v37, 16, 1
	v_bfe_u32 v50, v36, 16, 1
	v_add3_u32 v50, v36, v50, s11
	v_add3_u32 v49, v37, v49, s11
	v_add3_u32 v36, v40, v48, s11
	v_add3_u32 v37, v41, v43, s11
	v_bfe_u32 v40, v34, 16, 1
	v_bfe_u32 v41, v35, 16, 1
	v_bfe_u32 v43, v38, 16, 1
	v_bfe_u32 v48, v39, 16, 1
	v_add3_u32 v39, v39, v48, s11
	v_add3_u32 v38, v38, v43, s11
	v_add3_u32 v35, v35, v41, s11
	v_add3_u32 v34, v34, v40, s11
	v_lshrrev_b32_e32 v34, 16, v34
	v_lshrrev_b32_e32 v35, 16, v35
	v_lshrrev_b32_e32 v38, 16, v38
	v_lshrrev_b32_e32 v39, 16, v39
	v_add_co_u32_e32 v6, vcc, s28, v6
	v_and_or_b32 v37, v37, s23, v39
	v_and_or_b32 v36, v36, s23, v38
	v_and_or_b32 v35, v49, s23, v35
	v_and_or_b32 v34, v50, s23, v34
	v_addc_co_u32_e32 v7, vcc, 0, v7, vcc
	global_store_dwordx4 v[6:7], v[34:37], off offset:2048
	ds_read_b128 v[34:37], v74 offset:48
	s_nop 0
	ds_read_b128 v[38:41], v74 offset:32
	v_pk_mul_f32 v[10:11], v[52:53], v[10:11] op_sel_hi:[0,1]
	v_pk_mul_f32 v[48:49], v[52:53], v[166:167] op_sel_hi:[0,1]
	s_waitcnt lgkmcnt(0)
	v_mov_b32_e32 v50, v38
	v_mov_b32_e32 v51, v40
	v_mov_b32_e32 v40, v39
	v_mov_b32_e32 v38, v57
	v_mov_b32_e32 v39, v45
	v_pk_mul_f32 v[10:11], v[10:11], v[40:41]
	v_pk_mul_f32 v[38:39], v[52:53], v[38:39] op_sel_hi:[0,1]
	v_mov_b32_e32 v40, v34
	v_mov_b32_e32 v41, v36
	v_mov_b32_e32 v57, v44
	v_pk_mul_f32 v[38:39], v[38:39], v[40:41]
	v_pk_mul_f32 v[40:41], v[52:53], v[56:57] op_sel_hi:[0,1]
	v_mov_b32_e32 v36, v35
	v_pk_mul_f32 v[34:35], v[40:41], v[36:37]
	v_pk_mul_f32 v[48:49], v[48:49], v[50:51]
	v_bfe_u32 v36, v35, 16, 1
	v_bfe_u32 v37, v34, 16, 1
	v_bfe_u32 v40, v11, 16, 1
	v_bfe_u32 v41, v10, 16, 1
	v_add3_u32 v10, v10, v41, s11
	v_add3_u32 v11, v11, v40, s11
	v_add3_u32 v34, v34, v37, s11
	v_add3_u32 v35, v35, v36, s11
	v_bfe_u32 v36, v48, 16, 1
	v_bfe_u32 v37, v49, 16, 1
	v_bfe_u32 v40, v38, 16, 1
	v_bfe_u32 v41, v39, 16, 1
	v_add3_u32 v39, v39, v41, s11
	v_add3_u32 v38, v38, v40, s11
	v_add3_u32 v37, v49, v37, s11
	v_add3_u32 v36, v48, v36, s11
	v_lshrrev_b32_e32 v40, 16, v36
	v_lshrrev_b32_e32 v41, 16, v37
	v_lshrrev_b32_e32 v36, 16, v38
	v_lshrrev_b32_e32 v37, 16, v39
	v_and_or_b32 v37, v35, s23, v37
	v_and_or_b32 v36, v34, s23, v36
	v_and_or_b32 v35, v11, s23, v41
	v_and_or_b32 v34, v10, s23, v40
	v_pk_mul_f32 v[10:11], v[146:147], v[148:149] op_sel_hi:[1,0]
	v_and_b32_e32 v40, 0xffff0000, v28
	v_lshlrev_b32_e32 v41, 16, v32
	v_and_b32_e32 v44, 0xffff0000, v32
	v_lshlrev_b32_e32 v45, 16, v28
	v_pk_mul_f32 v[40:41], v[10:11], v[40:41] op_sel:[1,0] op_sel_hi:[0,1]
	v_and_b32_e32 v48, 0xffff0000, v20
	v_lshlrev_b32_e32 v49, 16, v20
	v_pk_fma_f32 v[40:41], v[10:11], v[44:45], v[40:41]
	global_store_dwordx4 v[6:7], v[34:37], off offset:2064
	v_pk_fma_f32 v[40:41], v[42:43], v[48:49], v[40:41] op_sel_hi:[0,1,1]
	v_and_b32_e32 v48, 0xffff0000, v29
	v_lshlrev_b32_e32 v49, 16, v33
	v_and_b32_e32 v28, 0xffff0000, v33
	v_pk_mul_f32 v[32:33], v[10:11], v[48:49] op_sel:[1,0] op_sel_hi:[0,1]
	ds_read_b128 v[48:51], v74 offset:16
	ds_read_b128 v[52:55], v74
	v_pk_mul_f32 v[34:35], v[10:11], v[198:199] op_sel:[1,0] op_sel_hi:[0,1]
	v_pk_fma_f32 v[34:35], v[10:11], v[200:201], v[34:35]
	v_lshlrev_b32_e32 v37, 16, v23
	v_lshlrev_b32_e32 v36, 16, v22
	v_pk_fma_f32 v[34:35], v[42:43], v[36:37], v[34:35] op_sel_hi:[0,1,1]
	v_pk_mul_f32 v[36:37], v[10:11], v[150:151] op_sel:[1,0] op_sel_hi:[0,1]
	v_pk_fma_f32 v[36:37], v[10:11], v[152:153], v[36:37]
	v_and_b32_e32 v23, 0xffff0000, v23
	v_and_b32_e32 v22, 0xffff0000, v22
	v_pk_fma_f32 v[22:23], v[42:43], v[22:23], v[36:37] op_sel_hi:[0,1,1]
	v_lshlrev_b32_e32 v29, 16, v29
	v_pk_mul_f32 v[56:57], v[10:11], v[140:141] op_sel:[1,0] op_sel_hi:[0,1]
	v_pk_mul_f32 v[36:37], v[34:35], v[34:35]
	v_pk_mul_f32 v[38:39], v[22:23], v[22:23]
	v_pk_fma_f32 v[28:29], v[10:11], v[28:29], v[32:33]
	v_pk_fma_f32 v[56:57], v[10:11], v[142:143], v[56:57]
	v_add_f32_e32 v36, v36, v38
	v_add_f32_e32 v36, v37, v36
	v_pk_mul_f32 v[72:73], v[10:11], v[132:133] op_sel:[1,0] op_sel_hi:[0,1]
	v_add_f32_e32 v36, v39, v36
	v_pk_fma_f32 v[72:73], v[10:11], v[134:135], v[72:73]
	v_and_b32_e32 v20, 0xffff0000, v21
	v_lshlrev_b32_e32 v21, 16, v21
	v_pk_fma_f32 v[28:29], v[42:43], v[20:21], v[28:29] op_sel_hi:[0,1,1]
	v_pk_mul_f32 v[44:45], v[40:41], v[40:41]
	v_pk_mul_f32 v[20:21], v[28:29], v[28:29]
	v_lshl_add_u64 v[6:7], s[76:77], 0, v[110:111]
	v_lshl_add_u64 v[110:111], v[110:111], 0, s[30:31]
	s_waitcnt lgkmcnt(0)
; __device__ __forceinline__ float sx(float v, int mask, int lane) { return __int_as_float(__builtin_amdgcn_ds_bpermute((lane ^ mask) << 2, __float_as_int(v))); }
; __device__ __forceinline__ float bflo(unsigned w) { return __uint_as_float(w << 16); }
; __device__ __forceinline__ float bfhi(unsigned w) { return __uint_as_float(w & 0xffff0000u); }
; __device__ __forceinline__ unsigned pk2(float lo, float hi) { return f2bf(lo) | (f2bf(hi) << 16); }
; __device__ __forceinline__ void dil_combine_load(float (&o)[16], float& rn, const bf16_t* p0, const bf16_t* p1, const bf16_t* xo, const float* lse0, const float* lse1, const float* lse2, int lane) {
;     ...
;     for (int j = 0; j < 2; ++j) { const u32x4 a = *(const u32x4*)(p0 + off + 8 * j), bq = *(const u32x4*)(p1 + off + 8 * j), cq = *(const u32x4*)(xo + off + 8 * j);
; #pragma unroll
;         for (int e = 0; e < 4; ++e) { o[8 * j + 2 * e] = w0 * bflo(a[e]) + w1 * bflo(bq[e]) + w2 * bflo(cq[e]); o[8 * j + 2 * e + 1] = w0 * bfhi(a[e]) + w1 * bfhi(bq[e]) + w2 * bfhi(cq[e]); } }
; #pragma unroll
;     for (int d = 0; d < 16; ++d) ss += o[d] * o[d];
;     ss += sx(ss, 1, lane); ss += sx(ss, 2, lane); ss += sx(ss, 4, lane);
;     rn = 1.0f / sqrtf(ss * (1.f / 128.f) + RMS_EPS);
; }
; __device__ __forceinline__ void dil_combine_store(const float (&o)[16], float rn, bf16_t* xo, const float* g_dil, int lane) {
;     const int h = lane >> 3, seg = lane & 7; const int off = h * 128 + seg * 16;
; #pragma unroll
;     for (int j = 0; j < 2; ++j) { u32x4 w;
; #pragma unroll
;         for (int e = 0; e < 4; ++e) w[e] = pk2(o[8 * j + 2 * e] * rn * g_dil[seg * 16 + 8 * j + 2 * e], o[8 * j + 2 * e + 1] * rn * g_dil[seg * 16 + 8 * j + 2 * e + 1]);
;         *(u32x4*)(xo + off + 8 * j) = w; }
	v_mov_b32_e32 v64, v48
	s_waitcnt lgkmcnt(0)
	v_mov_b32_e32 v32, v52
	v_mov_b32_e32 v33, v54
	v_mov_b32_e32 v54, v53
	v_lshlrev_b32_e32 v53, 16, v25
	v_lshlrev_b32_e32 v52, 16, v24
	v_pk_fma_f32 v[52:53], v[42:43], v[52:53], v[56:57] op_sel_hi:[0,1,1]
	v_pk_mul_f32 v[56:57], v[10:11], v[136:137] op_sel:[1,0] op_sel_hi:[0,1]
	v_and_b32_e32 v25, 0xffff0000, v25
	v_and_b32_e32 v24, 0xffff0000, v24
	v_pk_fma_f32 v[56:57], v[10:11], v[138:139], v[56:57]
	v_mov_b32_e32 v65, v50
	v_pk_fma_f32 v[24:25], v[42:43], v[24:25], v[56:57] op_sel_hi:[0,1,1]
	v_pk_mul_f32 v[56:57], v[52:53], v[52:53]
	v_pk_mul_f32 v[60:61], v[24:25], v[24:25]
	v_mov_b32_e32 v50, v49
	v_lshlrev_b32_e32 v49, 16, v19
	v_lshlrev_b32_e32 v48, 16, v18
	v_add_f32_e32 v36, v56, v36
	v_pk_fma_f32 v[48:49], v[42:43], v[48:49], v[72:73] op_sel_hi:[0,1,1]
	v_pk_mul_f32 v[72:73], v[10:11], v[128:129] op_sel:[1,0] op_sel_hi:[0,1]
	v_add_f32_e32 v36, v60, v36
	v_and_b32_e32 v19, 0xffff0000, v19
	v_and_b32_e32 v18, 0xffff0000, v18
	v_pk_fma_f32 v[10:11], v[10:11], v[130:131], v[72:73]
	v_add_f32_e32 v36, v57, v36
	v_pk_fma_f32 v[10:11], v[42:43], v[18:19], v[10:11] op_sel_hi:[0,1,1]
	v_pk_mul_f32 v[18:19], v[48:49], v[48:49]
	v_add_f32_e32 v36, v61, v36
	v_pk_mul_f32 v[42:43], v[10:11], v[10:11]
	v_add_f32_e32 v18, v36, v18
	v_add_f32_e32 v18, v42, v18
	v_add_f32_e32 v18, v19, v18
	v_add_f32_e32 v18, v43, v18
	v_add_f32_e32 v18, v45, v18
	v_add_f32_e32 v18, v44, v18
	v_add_f32_e32 v18, v21, v18
	v_add_f32_e32 v18, v20, v18
	ds_bpermute_b32 v19, v127, v18
	s_waitcnt lgkmcnt(0)
	v_add_f32_e32 v18, v18, v19
	ds_bpermute_b32 v19, v145, v18
	s_waitcnt lgkmcnt(0)
	v_add_f32_e32 v18, v18, v19
	ds_bpermute_b32 v19, v149, v18
	s_waitcnt lgkmcnt(0)
	v_add_f32_e32 v18, v18, v19
	v_fmamk_f32 v18, v18, 0x3c000000, v244
	v_cmp_gt_f32_e32 vcc, s3, v18
	v_mul_f32_e32 v19, 0x4f800000, v18
	s_nop 0
	v_cndmask_b32_e32 v18, v18, v19, vcc
	v_sqrt_f32_e32 v19, v18
	s_nop 0
	v_add_u32_e32 v20, -1, v19
	v_fma_f32 v21, -v20, v19, v18
	v_cmp_ge_f32_e64 s[4:5], 0, v21
	v_add_u32_e32 v21, 1, v19
	s_nop 0
	v_cndmask_b32_e64 v20, v19, v20, s[4:5]
	v_fma_f32 v19, -v21, v19, v18
	v_cmp_lt_f32_e64 s[4:5], 0, v19
	s_nop 1
	v_cndmask_b32_e64 v19, v20, v21, s[4:5]
	v_mul_f32_e32 v20, 0x37800000, v19
	v_cndmask_b32_e32 v19, v19, v20, vcc
	v_cmp_class_f32_e32 vcc, v18, v245
	s_nop 1
	v_cndmask_b32_e32 v18, v19, v18, vcc
	v_div_scale_f32 v19, s[0:1], v18, v18, 1.0
	v_rcp_f32_e32 v20, v19
	s_nop 0
	v_fma_f32 v21, -v19, v20, 1.0
	v_fmac_f32_e32 v20, v21, v20
	v_div_scale_f32 v21, vcc, 1.0, v18, 1.0
	v_mul_f32_e32 v36, v21, v20
	v_fma_f32 v37, -v19, v36, v21
	v_fmac_f32_e32 v36, v37, v20
	v_fma_f32 v19, -v19, v36, v21
	v_div_fmas_f32 v19, v19, v20, v36
	v_div_fixup_f32 v36, v19, v18, 1.0
	v_pk_mul_f32 v[20:21], v[36:37], v[22:23] op_sel_hi:[0,1]
	v_pk_mul_f32 v[24:25], v[36:37], v[24:25] op_sel_hi:[0,1]
	v_pk_mul_f32 v[18:19], v[36:37], v[34:35] op_sel_hi:[0,1]
	v_pk_mul_f32 v[20:21], v[20:21], v[54:55]
	v_pk_mul_f32 v[22:23], v[36:37], v[52:53] op_sel_hi:[0,1]
	v_pk_mul_f32 v[24:25], v[24:25], v[50:51]
	v_pk_mul_f32 v[18:19], v[18:19], v[32:33]
	v_pk_mul_f32 v[22:23], v[22:23], v[64:65]
	v_bfe_u32 v32, v25, 16, 1
	v_bfe_u32 v33, v24, 16, 1
	v_bfe_u32 v34, v21, 16, 1
	v_bfe_u32 v35, v20, 16, 1
	v_add3_u32 v35, v20, v35, s11
	v_add3_u32 v34, v21, v34, s11
	v_add3_u32 v20, v24, v33, s11
	v_add3_u32 v21, v25, v32, s11
	v_bfe_u32 v24, v18, 16, 1
	v_bfe_u32 v25, v19, 16, 1
	v_bfe_u32 v32, v22, 16, 1
	v_bfe_u32 v33, v23, 16, 1
	v_add3_u32 v23, v23, v33, s11
	v_add3_u32 v22, v22, v32, s11
	v_add3_u32 v19, v19, v25, s11
	v_add3_u32 v18, v18, v24, s11
	v_lshrrev_b32_e32 v18, 16, v18
	v_lshrrev_b32_e32 v19, 16, v19
	v_lshrrev_b32_e32 v22, 16, v22
	v_lshrrev_b32_e32 v23, 16, v23
	v_add_co_u32_e32 v6, vcc, s28, v6
	v_and_or_b32 v21, v21, s23, v23
	v_and_or_b32 v20, v20, s23, v22
	v_and_or_b32 v19, v34, s23, v19
	v_and_or_b32 v18, v35, s23, v18
	v_addc_co_u32_e32 v7, vcc, 0, v7, vcc
	global_store_dwordx4 v[6:7], v[18:21], off offset:2048
	ds_read_b128 v[18:21], v74 offset:48
	s_nop 0
	ds_read_b128 v[22:25], v74 offset:32
	v_pk_mul_f32 v[10:11], v[36:37], v[10:11] op_sel_hi:[0,1]
	v_pk_mul_f32 v[32:33], v[36:37], v[48:49] op_sel_hi:[0,1]
	s_waitcnt lgkmcnt(0)
; __device__ __forceinline__ float sx(float v, int mask, int lane) { return __int_as_float(__builtin_amdgcn_ds_bpermute((lane ^ mask) << 2, __float_as_int(v))); }
; __device__ __forceinline__ float bflo(unsigned w) { return __uint_as_float(w << 16); }
; __device__ __forceinline__ float bfhi(unsigned w) { return __uint_as_float(w & 0xffff0000u); }
; __device__ __forceinline__ unsigned pk2(float lo, float hi) { return f2bf(lo) | (f2bf(hi) << 16); }
; __device__ __forceinline__ void dil_combine_load(float (&o)[16], float& rn, const bf16_t* p0, const bf16_t* p1, const bf16_t* xo, const float* lse0, const float* lse1, const float* lse2, int lane) {
;     ...
;     for (int j = 0; j < 2; ++j) { const u32x4 a = *(const u32x4*)(p0 + off + 8 * j), bq = *(const u32x4*)(p1 + off + 8 * j), cq = *(const u32x4*)(xo + off + 8 * j);
; #pragma unroll
;         for (int e = 0; e < 4; ++e) { o[8 * j + 2 * e] = w0 * bflo(a[e]) + w1 * bflo(bq[e]) + w2 * bflo(cq[e]); o[8 * j + 2 * e + 1] = w0 * bfhi(a[e]) + w1 * bfhi(bq[e]) + w2 * bfhi(cq[e]); } }
; #pragma unroll
;     for (int d = 0; d < 16; ++d) ss += o[d] * o[d];
;     ss += sx(ss, 1, lane); ss += sx(ss, 2, lane); ss += sx(ss, 4, lane);
;     rn = 1.0f / sqrtf(ss * (1.f / 128.f) + RMS_EPS);
; }
; __device__ __forceinline__ void dil_combine_store(const float (&o)[16], float rn, bf16_t* xo, const float* g_dil, int lane) {
;     const int h = lane >> 3, seg = lane & 7; const int off = h * 128 + seg * 16;
; #pragma unroll
;     for (int j = 0; j < 2; ++j) { u32x4 w;
; #pragma unroll
;         for (int e = 0; e < 4; ++e) w[e] = pk2(o[8 * j + 2 * e] * rn * g_dil[seg * 16 + 8 * j + 2 * e], o[8 * j + 2 * e + 1] * rn * g_dil[seg * 16 + 8 * j + 2 * e + 1]);
;         *(u32x4*)(xo + off + 8 * j) = w; }
	v_mov_b32_e32 v34, v22
	v_mov_b32_e32 v35, v24
	v_mov_b32_e32 v24, v23
	v_mov_b32_e32 v22, v41
	v_mov_b32_e32 v23, v29
	v_pk_mul_f32 v[10:11], v[10:11], v[24:25]
	v_pk_mul_f32 v[22:23], v[36:37], v[22:23] op_sel_hi:[0,1]
	v_mov_b32_e32 v24, v18
	v_mov_b32_e32 v25, v20
	v_mov_b32_e32 v41, v28
	v_pk_mul_f32 v[22:23], v[22:23], v[24:25]
	v_pk_mul_f32 v[24:25], v[36:37], v[40:41] op_sel_hi:[0,1]
	v_mov_b32_e32 v20, v19
	v_pk_mul_f32 v[18:19], v[24:25], v[20:21]
	v_pk_mul_f32 v[32:33], v[32:33], v[34:35]
	v_bfe_u32 v20, v19, 16, 1
	v_bfe_u32 v21, v18, 16, 1
	v_bfe_u32 v24, v11, 16, 1
	v_bfe_u32 v25, v10, 16, 1
	v_add3_u32 v10, v10, v25, s11
	v_add3_u32 v11, v11, v24, s11
	v_add3_u32 v18, v18, v21, s11
	v_add3_u32 v19, v19, v20, s11
	v_bfe_u32 v20, v32, 16, 1
	v_bfe_u32 v21, v33, 16, 1
	v_bfe_u32 v24, v22, 16, 1
	v_bfe_u32 v25, v23, 16, 1
	v_add3_u32 v23, v23, v25, s11
	v_add3_u32 v22, v22, v24, s11
	v_add3_u32 v21, v33, v21, s11
	v_add3_u32 v20, v32, v20, s11
	v_lshrrev_b32_e32 v24, 16, v20
	v_lshrrev_b32_e32 v25, 16, v21
	v_lshrrev_b32_e32 v20, 16, v22
	v_lshrrev_b32_e32 v21, 16, v23
	v_and_or_b32 v21, v19, s23, v21
	v_and_or_b32 v20, v18, s23, v20
	v_and_or_b32 v19, v11, s23, v25
	v_and_or_b32 v18, v10, s23, v24
	v_pk_mul_f32 v[10:11], v[124:125], v[126:127] op_sel_hi:[1,0]
	global_store_dwordx4 v[6:7], v[18:21], off offset:2064
	v_pk_mul_f32 v[6:7], v[10:11], v[158:159] op_sel:[1,0] op_sel_hi:[0,1]
	v_pk_fma_f32 v[6:7], v[10:11], v[160:161], v[6:7]
	v_lshlrev_b32_e32 v21, 16, v15
	v_lshlrev_b32_e32 v20, 16, v14
	v_pk_fma_f32 v[20:21], v[0:1], v[20:21], v[6:7] op_sel_hi:[0,1,1]
	v_pk_mul_f32 v[6:7], v[10:11], v[154:155] op_sel:[1,0] op_sel_hi:[0,1]
	v_pk_fma_f32 v[6:7], v[10:11], v[156:157], v[6:7]
	v_and_b32_e32 v15, 0xffff0000, v15
	v_and_b32_e32 v14, 0xffff0000, v14
	v_pk_fma_f32 v[14:15], v[0:1], v[14:15], v[6:7] op_sel_hi:[0,1,1]
	v_and_b32_e32 v6, 0xffff0000, v8
	v_lshlrev_b32_e32 v7, 16, v12
	v_and_b32_e32 v28, 0xffff0000, v12
	v_lshlrev_b32_e32 v29, 16, v8
	v_pk_mul_f32 v[6:7], v[10:11], v[6:7] op_sel:[1,0] op_sel_hi:[0,1]
	v_and_b32_e32 v32, 0xffff0000, v4
	v_lshlrev_b32_e32 v33, 16, v4
	v_pk_fma_f32 v[6:7], v[10:11], v[28:29], v[6:7]
	v_and_b32_e32 v8, 0xffff0000, v13
	v_pk_fma_f32 v[6:7], v[0:1], v[32:33], v[6:7] op_sel_hi:[0,1,1]
	v_and_b32_e32 v32, 0xffff0000, v9
	v_lshlrev_b32_e32 v33, 16, v13
	v_pk_mul_f32 v[12:13], v[10:11], v[32:33] op_sel:[1,0] op_sel_hi:[0,1]
	ds_read_b128 v[32:35], v74 offset:16
	ds_read_b128 v[36:39], v74
	v_lshlrev_b32_e32 v9, 16, v9
	v_pk_fma_f32 v[8:9], v[10:11], v[8:9], v[12:13]
	v_lshlrev_b32_e32 v13, 16, v17
	v_lshlrev_b32_e32 v12, 16, v16
	v_and_b32_e32 v17, 0xffff0000, v17
	v_and_b32_e32 v16, 0xffff0000, v16
	v_pk_mul_f32 v[22:23], v[20:21], v[20:21]
	v_pk_mul_f32 v[24:25], v[14:15], v[14:15]
	v_and_b32_e32 v4, 0xffff0000, v5
	v_lshlrev_b32_e32 v5, 16, v5
	v_pk_fma_f32 v[8:9], v[0:1], v[4:5], v[8:9] op_sel_hi:[0,1,1]
	v_pk_mul_f32 v[28:29], v[6:7], v[6:7]
	v_pk_mul_f32 v[4:5], v[8:9], v[8:9]
	v_lshl_add_u64 v[18:19], s[76:77], 0, v[102:103]
	v_lshl_add_u64 v[102:103], v[102:103], 0, s[30:31]
	s_waitcnt lgkmcnt(0)
	v_mov_b32_e32 v42, v32
	s_waitcnt lgkmcnt(0)
	v_mov_b32_e32 v40, v36
	v_mov_b32_e32 v41, v38
	v_mov_b32_e32 v38, v37
	v_pk_mul_f32 v[36:37], v[10:11], v[46:47] op_sel:[1,0] op_sel_hi:[0,1]
	v_pk_fma_f32 v[36:37], v[10:11], v[58:59], v[36:37]
	v_mov_b32_e32 v43, v34
	v_pk_fma_f32 v[36:37], v[0:1], v[12:13], v[36:37] op_sel_hi:[0,1,1]
	v_pk_mul_f32 v[12:13], v[10:11], v[26:27] op_sel:[1,0] op_sel_hi:[0,1]
	v_pk_fma_f32 v[12:13], v[10:11], v[30:31], v[12:13]
	v_mov_b32_e32 v34, v33
	v_pk_mul_f32 v[32:33], v[10:11], v[68:69] op_sel:[1,0] op_sel_hi:[0,1]
	v_pk_fma_f32 v[16:17], v[0:1], v[16:17], v[12:13] op_sel_hi:[0,1,1]
	v_lshlrev_b32_e32 v13, 16, v3
	v_lshlrev_b32_e32 v12, 16, v2
	v_pk_fma_f32 v[32:33], v[10:11], v[70:71], v[32:33]
	v_and_b32_e32 v3, 0xffff0000, v3
	v_pk_fma_f32 v[12:13], v[0:1], v[12:13], v[32:33] op_sel_hi:[0,1,1]
	v_pk_mul_f32 v[32:33], v[10:11], v[62:63] op_sel:[1,0] op_sel_hi:[0,1]
	v_and_b32_e32 v2, 0xffff0000, v2
	v_pk_fma_f32 v[10:11], v[10:11], v[66:67], v[32:33]
	v_pk_mul_f32 v[26:27], v[36:37], v[36:37]
	v_pk_fma_f32 v[10:11], v[0:1], v[2:3], v[10:11] op_sel_hi:[0,1,1]
	v_add_f32_e32 v0, v22, v24
	v_add_f32_e32 v0, v23, v0
	v_add_f32_e32 v0, v25, v0
	v_pk_mul_f32 v[30:31], v[16:17], v[16:17]
	v_add_f32_e32 v0, v26, v0
	v_add_f32_e32 v0, v30, v0
	v_add_f32_e32 v0, v27, v0
	v_pk_mul_f32 v[2:3], v[12:13], v[12:13]
	v_add_f32_e32 v0, v31, v0
	v_pk_mul_f32 v[32:33], v[10:11], v[10:11]
	v_add_f32_e32 v0, v0, v2
	v_add_f32_e32 v0, v32, v0
	v_add_f32_e32 v0, v3, v0
	v_add_f32_e32 v0, v33, v0
	v_add_f32_e32 v0, v29, v0
	v_add_f32_e32 v0, v28, v0
	v_add_f32_e32 v0, v5, v0
	v_add_f32_e32 v0, v4, v0
	ds_bpermute_b32 v2, v127, v0
	s_waitcnt lgkmcnt(0)
; __device__ __forceinline__ float sx(float v, int mask, int lane) { return __int_as_float(__builtin_amdgcn_ds_bpermute((lane ^ mask) << 2, __float_as_int(v))); }
; __device__ __forceinline__ float bflo(unsigned w) { return __uint_as_float(w << 16); }
; __device__ __forceinline__ float bfhi(unsigned w) { return __uint_as_float(w & 0xffff0000u); }
; __device__ __forceinline__ unsigned pk2(float lo, float hi) { return f2bf(lo) | (f2bf(hi) << 16); }
; __device__ __forceinline__ void dil_combine_load(float (&o)[16], float& rn, const bf16_t* p0, const bf16_t* p1, const bf16_t* xo, const float* lse0, const float* lse1, const float* lse2, int lane) {
;     ...
;     for (int j = 0; j < 2; ++j) { const u32x4 a = *(const u32x4*)(p0 + off + 8 * j), bq = *(const u32x4*)(p1 + off + 8 * j), cq = *(const u32x4*)(xo + off + 8 * j);
; #pragma unroll
;         for (int e = 0; e < 4; ++e) { o[8 * j + 2 * e] = w0 * bflo(a[e]) + w1 * bflo(bq[e]) + w2 * bflo(cq[e]); o[8 * j + 2 * e + 1] = w0 * bfhi(a[e]) + w1 * bfhi(bq[e]) + w2 * bfhi(cq[e]); } }
; #pragma unroll
;     for (int d = 0; d < 16; ++d) ss += o[d] * o[d];
;     ss += sx(ss, 1, lane); ss += sx(ss, 2, lane); ss += sx(ss, 4, lane);
;     rn = 1.0f / sqrtf(ss * (1.f / 128.f) + RMS_EPS);
; }
; __device__ __forceinline__ void dil_combine_store(const float (&o)[16], float rn, bf16_t* xo, const float* g_dil, int lane) {
;     const int h = lane >> 3, seg = lane & 7; const int off = h * 128 + seg * 16;
; #pragma unroll
;     for (int j = 0; j < 2; ++j) { u32x4 w;
; #pragma unroll
;         for (int e = 0; e < 4; ++e) w[e] = pk2(o[8 * j + 2 * e] * rn * g_dil[seg * 16 + 8 * j + 2 * e], o[8 * j + 2 * e + 1] * rn * g_dil[seg * 16 + 8 * j + 2 * e + 1]);
;         *(u32x4*)(xo + off + 8 * j) = w; }
; __global__ void __launch_bounds__(NWAVES * 64, 2) mega_fwd(Params P) {
;     ...
;           for (int m = gw; m < TOK; m += 4 * NGW) { float o[4][16], rn[4];
; #pragma unroll
;               for (int j = 0; j < 4; ++j) { const int mm = m + j * NGW; dil_combine_load(o[j], rn[j], PART0 + (size_t)mm * 1024, PART1 + (size_t)mm * 1024, XB + (size_t)mm * DM + 1024, LSE + (size_t)mm * 8, LSE + (size_t)(TOK + mm) * 8, LSE + (size_t)(2 * TOK + mm) * 8, lane); }
; #pragma unroll
;               for (int j = 0; j < 4; ++j) { const int mm = m + j * NGW; dil_combine_store(o[j], rn[j], XB + (size_t)mm * DM + 1024, gdl, lane); } } }
	v_add_f32_e32 v0, v0, v2
	ds_bpermute_b32 v2, v145, v0
	s_waitcnt lgkmcnt(0)
	v_add_f32_e32 v0, v0, v2
	ds_bpermute_b32 v2, v149, v0
	s_waitcnt lgkmcnt(0)
	v_add_f32_e32 v0, v0, v2
	v_fmamk_f32 v0, v0, 0x3c000000, v244
	v_cmp_gt_f32_e32 vcc, s3, v0
	v_mul_f32_e32 v2, 0x4f800000, v0
	s_nop 0
	v_cndmask_b32_e32 v0, v0, v2, vcc
	v_sqrt_f32_e32 v2, v0
	s_nop 0
	v_add_u32_e32 v3, -1, v2
	v_fma_f32 v4, -v3, v2, v0
	v_cmp_ge_f32_e64 s[4:5], 0, v4
	v_add_u32_e32 v4, 1, v2
	s_nop 0
	v_cndmask_b32_e64 v3, v2, v3, s[4:5]
	v_fma_f32 v2, -v4, v2, v0
	v_cmp_lt_f32_e64 s[4:5], 0, v2
	s_nop 1
	v_cndmask_b32_e64 v2, v3, v4, s[4:5]
	v_mul_f32_e32 v3, 0x37800000, v2
	v_cndmask_b32_e32 v2, v2, v3, vcc
	v_cmp_class_f32_e32 vcc, v0, v245
	s_nop 1
	v_cndmask_b32_e32 v0, v2, v0, vcc
	v_div_scale_f32 v2, s[0:1], v0, v0, 1.0
	v_rcp_f32_e32 v3, v2
	s_nop 0
	v_fma_f32 v4, -v2, v3, 1.0
	v_fmac_f32_e32 v3, v4, v3
	v_div_scale_f32 v4, vcc, 1.0, v0, 1.0
	v_mul_f32_e32 v5, v4, v3
	v_fma_f32 v22, -v2, v5, v4
	v_fmac_f32_e32 v5, v22, v3
	v_fma_f32 v2, -v2, v5, v4
	v_div_fmas_f32 v2, v2, v3, v5
	v_div_fixup_f32 v0, v2, v0, 1.0
	v_pk_mul_f32 v[4:5], v[0:1], v[14:15] op_sel_hi:[0,1]
	v_pk_mul_f32 v[16:17], v[0:1], v[16:17] op_sel_hi:[0,1]
	v_pk_mul_f32 v[4:5], v[4:5], v[38:39]
	v_pk_mul_f32 v[14:15], v[0:1], v[36:37] op_sel_hi:[0,1]
	v_pk_mul_f32 v[16:17], v[16:17], v[34:35]
	v_pk_mul_f32 v[2:3], v[0:1], v[20:21] op_sel_hi:[0,1]
	v_pk_mul_f32 v[14:15], v[14:15], v[42:43]
	v_bfe_u32 v20, v17, 16, 1
	v_bfe_u32 v22, v5, 16, 1
	v_pk_mul_f32 v[2:3], v[2:3], v[40:41]
	v_bfe_u32 v21, v16, 16, 1
	v_bfe_u32 v23, v4, 16, 1
	v_add3_u32 v22, v5, v22, s11
	v_add3_u32 v5, v17, v20, s11
	v_bfe_u32 v20, v14, 16, 1
	v_add3_u32 v23, v4, v23, s11
	v_add3_u32 v4, v16, v21, s11
	v_bfe_u32 v16, v2, 16, 1
	v_bfe_u32 v17, v3, 16, 1
	v_bfe_u32 v21, v15, 16, 1
	v_add3_u32 v14, v14, v20, s11
	v_add3_u32 v15, v15, v21, s11
	v_add3_u32 v3, v3, v17, s11
	v_add3_u32 v2, v2, v16, s11
	v_lshrrev_b32_e32 v14, 16, v14
	v_lshrrev_b32_e32 v2, 16, v2
	v_lshrrev_b32_e32 v3, 16, v3
	v_lshrrev_b32_e32 v15, 16, v15
	v_and_or_b32 v4, v4, s23, v14
	v_add_co_u32_e32 v14, vcc, s28, v18
	v_and_or_b32 v5, v5, s23, v15
	v_and_or_b32 v3, v22, s23, v3
	v_and_or_b32 v2, v23, s23, v2
	v_addc_co_u32_e32 v15, vcc, 0, v19, vcc
	global_store_dwordx4 v[14:15], v[2:5], off offset:2048
	ds_read_b128 v[2:5], v74 offset:48
	s_nop 0
	ds_read_b128 v[16:19], v74 offset:32
	v_pk_mul_f32 v[10:11], v[0:1], v[10:11] op_sel_hi:[0,1]
	v_pk_mul_f32 v[12:13], v[0:1], v[12:13] op_sel_hi:[0,1]
	s_waitcnt lgkmcnt(0)
	v_mov_b32_e32 v20, v16
	v_mov_b32_e32 v21, v18
	v_mov_b32_e32 v18, v17
	v_mov_b32_e32 v16, v7
	v_mov_b32_e32 v7, v8
	v_pk_mul_f32 v[10:11], v[10:11], v[18:19]
	v_mov_b32_e32 v17, v9
	v_mov_b32_e32 v19, v4
	v_pk_mul_f32 v[6:7], v[0:1], v[6:7] op_sel_hi:[0,1]
	v_mov_b32_e32 v4, v3
	v_pk_mul_f32 v[16:17], v[0:1], v[16:17] op_sel_hi:[0,1]
	v_mov_b32_e32 v18, v2
	v_pk_mul_f32 v[2:3], v[6:7], v[4:5]
	v_pk_mul_f32 v[12:13], v[12:13], v[20:21]
	v_pk_mul_f32 v[16:17], v[16:17], v[18:19]
	v_bfe_u32 v0, v3, 16, 1
	v_bfe_u32 v4, v2, 16, 1
	v_bfe_u32 v5, v11, 16, 1
	v_add3_u32 v7, v11, v5, s11
	v_add3_u32 v2, v2, v4, s11
	v_add3_u32 v0, v3, v0, s11
	v_bfe_u32 v3, v12, 16, 1
	v_bfe_u32 v4, v13, 16, 1
	v_bfe_u32 v5, v16, 16, 1
	v_bfe_u32 v8, v17, 16, 1
	v_bfe_u32 v6, v10, 16, 1
	v_add3_u32 v8, v17, v8, s11
	v_add3_u32 v5, v16, v5, s11
	v_add3_u32 v4, v13, v4, s11
	v_add3_u32 v3, v12, v3, s11
	v_add3_u32 v6, v10, v6, s11
	v_lshrrev_b32_e32 v9, 16, v3
	v_lshrrev_b32_e32 v3, 16, v4
	v_lshrrev_b32_e32 v4, 16, v5
	v_lshrrev_b32_e32 v5, 16, v8
	v_and_or_b32 v5, v0, s23, v5
	v_and_or_b32 v4, v2, s23, v4
	v_and_or_b32 v3, v7, s23, v3
	v_and_or_b32 v2, v6, s23, v9
	global_store_dwordx4 v[14:15], v[2:5], off offset:2064
	s_cbranch_scc0 .LBB0_409

; __device__ __forceinline__ void ln_row(const float* xin, float* yout, bf16_t* ybf, const float* g, const float* b, int lane) {
;     const f32x4* xr = (const f32x4*)xin + lane;
;     f32x4 v[8]; float s = 0.f;
; #pragma unroll
;     for (int j = 0; j < 8; ++j) { v[j] = xr[64 * j]; s += (v[j][0] + v[j][1]) + (v[j][2] + v[j][3]); }
;     const float mean = wave_sum(s, lane) * (1.f / DM); float s2 = 0.f;
; #pragma unroll
;     for (int j = 0; j < 8; ++j) { v[j] = v[j] - mean; s2 += (v[j][0] * v[j][0] + v[j][1] * v[j][1]) + (v[j][2] * v[j][2] + v[j][3] * v[j][3]); }
;     const float rstd = 1.f / sqrtf(wave_sum(s2, lane) * (1.f / DM) + LN_EPS);
; __global__ void __launch_bounds__(NWAVES * 64, 2) mega_fwd(Params P) {
;     ...
;     { PH_IDS
;       for (int m = gw; m < TOK; m += NGW) ln_row(H + (size_t)m * DM, H + (size_t)m * DM, (bf16_t*)nullptr, P.in[21] + (NLAYER - 1) * DM, P.in[22] + (NLAYER - 1) * DM, lane); }
.LBB0_1298:
	global_load_dwordx4 v[8:11], v[52:53], off offset:-3072 nt
	global_load_dwordx4 v[12:15], v[52:53], off offset:-2048 nt
	global_load_dwordx4 v[4:7], v[52:53], off offset:-1024 nt
	v_add_co_u32_e32 v54, vcc, 0xfffff000, v52
	global_load_dwordx4 v[0:3], v[52:53], off nt
	s_nop 0
	v_addc_co_u32_e32 v55, vcc, -1, v53, vcc
	global_load_dwordx4 v[28:31], v[54:55], off offset:-3072 nt
	global_load_dwordx4 v[24:27], v[54:55], off offset:-2048 nt
	global_load_dwordx4 v[20:23], v[54:55], off offset:-1024 nt
	global_load_dwordx4 v[16:19], v[52:53], off offset:-4096 nt
	s_addk_i32 s4, 0x800
	s_cmpk_gt_i32 s4, 0x77ff
	s_waitcnt vmcnt(7)
	v_mov_b32_e32 v67, v10
	s_waitcnt vmcnt(6)
	v_mov_b32_e32 v70, v13
	v_mov_b32_e32 v71, v14
	v_mov_b32_e32 v72, v12
	v_mov_b32_e32 v73, v15
	s_waitcnt vmcnt(5)
	v_add_f32_e32 v74, v4, v5
	v_add_f32_e32 v76, v6, v7
	s_waitcnt vmcnt(4)
	v_mov_b32_e32 v75, v2
	v_mov_b32_e32 v77, v3
	v_pk_add_f32 v[70:71], v[70:71], v[72:73]
	v_pk_add_f32 v[72:73], v[74:75], v[76:77]
	s_waitcnt vmcnt(3)
	v_mov_b32_e32 v74, v28
	s_waitcnt vmcnt(2)
	v_mov_b32_e32 v75, v24
	v_mov_b32_e32 v76, v29
	v_mov_b32_e32 v77, v25
	v_mov_b32_e32 v78, v30
	v_mov_b32_e32 v79, v26
	v_mov_b32_e32 v80, v31
	v_mov_b32_e32 v81, v27
	v_mov_b32_e32 v69, v11
	s_waitcnt vmcnt(1)
	v_mov_b32_e32 v82, v21
	v_mov_b32_e32 v83, v22
	v_mov_b32_e32 v84, v20
	v_mov_b32_e32 v85, v23
	s_waitcnt vmcnt(0)
	v_add_f32_e32 v66, v16, v17
	v_add_f32_e32 v68, v18, v19
	v_pk_add_f32 v[74:75], v[74:75], v[76:77]
	v_pk_add_f32 v[76:77], v[78:79], v[80:81]
	v_pk_add_f32 v[78:79], v[82:83], v[84:85]
	v_pk_add_f32 v[66:67], v[66:67], v[68:69]
	v_pk_add_f32 v[68:69], v[74:75], v[76:77]
	v_pk_add_f32 v[74:75], v[78:79], v[78:79] op_sel:[0,1] op_sel_hi:[1,0]
	v_add_f32_e32 v64, 0, v68
	v_mov_b32_e32 v65, v8
	v_mov_b32_e32 v75, v9
	v_add_f32_e32 v64, v64, v69
	v_pk_add_f32 v[64:65], v[64:65], v[74:75]
	v_pk_add_f32 v[70:71], v[70:71], v[70:71] op_sel:[0,1] op_sel_hi:[1,0]
	v_pk_add_f32 v[64:65], v[64:65], v[66:67]
	v_mov_b32_e32 v71, v1
	v_pk_add_f32 v[64:65], v[64:65], v[64:65] op_sel:[0,1] op_sel_hi:[1,0]
	s_nop 0
	v_mov_b32_e32 v65, v0
	v_pk_add_f32 v[64:65], v[64:65], v[70:71]
	s_nop 0
	v_pk_add_f32 v[64:65], v[64:65], v[72:73]
	s_nop 0
	v_add_f32_e32 v64, v64, v65
	ds_bpermute_b32 v65, v56, v64
	s_waitcnt lgkmcnt(0)
	v_add_f32_e32 v64, v64, v65
	ds_bpermute_b32 v65, v57, v64
	s_waitcnt lgkmcnt(0)
	v_add_f32_e32 v64, v64, v65
	ds_bpermute_b32 v65, v58, v64
	s_waitcnt lgkmcnt(0)
	v_add_f32_e32 v64, v64, v65
	ds_bpermute_b32 v65, v59, v64
	s_waitcnt lgkmcnt(0)
	v_add_f32_e32 v64, v64, v65
	ds_bpermute_b32 v65, v60, v64
	s_waitcnt lgkmcnt(0)
	v_add_f32_e32 v64, v64, v65
	ds_bpermute_b32 v65, v61, v64
	s_waitcnt lgkmcnt(0)
	v_add_f32_e32 v87, v64, v65
	v_fmamk_f32 v31, v87, 0xba000000, v31
	v_fmamk_f32 v29, v87, 0xba000000, v29
	v_fmamk_f32 v27, v87, 0xba000000, v27
	v_fmamk_f32 v25, v87, 0xba000000, v25
	v_fmamk_f32 v30, v87, 0xba000000, v30
	v_fmac_f32_e32 v28, 0xba000000, v87
	v_fmamk_f32 v26, v87, 0xba000000, v26
	v_fmac_f32_e32 v24, 0xba000000, v87
	v_fmamk_f32 v21, v87, 0xba000000, v21
	v_fmamk_f32 v20, v87, 0xba000000, v20
	v_fmamk_f32 v23, v87, 0xba000000, v23
	v_fmac_f32_e32 v22, 0xba000000, v87
	v_mov_b32_e32 v66, v29
	v_mov_b32_e32 v67, v25
	v_mov_b32_e32 v70, v31
	v_mov_b32_e32 v71, v27
	v_mov_b32_e32 v64, v28
	v_mov_b32_e32 v65, v24
	v_mov_b32_e32 v68, v30
	v_mov_b32_e32 v69, v26
	v_pk_mul_f32 v[72:73], v[22:23], v[22:23]
	v_pk_mul_f32 v[74:75], v[20:21], v[20:21]
	v_pk_mul_f32 v[66:67], v[66:67], v[66:67]
	v_pk_mul_f32 v[70:71], v[70:71], v[70:71]
	v_fmamk_f32 v16, v87, 0xba000000, v16
	v_fmac_f32_e32 v18, 0xba000000, v87
	v_pk_mov_b32 v[88:89], v[74:75], v[72:73] op_sel:[1,0]
	v_mov_b32_e32 v75, v73
	v_pk_fma_f32 v[64:65], v[64:65], v[64:65], v[66:67]
	v_pk_fma_f32 v[66:67], v[68:69], v[68:69], v[70:71]
	v_fmamk_f32 v17, v87, 0xba000000, v17
	v_fmamk_f32 v19, v87, 0xba000000, v19
	v_mul_f32_e32 v76, v16, v16
	v_mul_f32_e32 v78, v18, v18
	v_pk_add_f32 v[68:69], v[88:89], v[74:75]
	v_pk_add_f32 v[64:65], v[64:65], v[66:67]
	v_fmamk_f32 v11, v87, 0xba000000, v11
	v_fmamk_f32 v10, v87, 0xba000000, v10
	v_fmamk_f32 v9, v87, 0xba000000, v9
	v_fmac_f32_e32 v8, 0xba000000, v87
	v_fmamk_f32 v13, v87, 0xba000000, v13
	v_fmamk_f32 v12, v87, 0xba000000, v12
	v_fmamk_f32 v15, v87, 0xba000000, v15
	v_fmac_f32_e32 v14, 0xba000000, v87
	v_pk_fma_f32 v[72:73], v[16:17], v[16:17], v[76:77] op_sel_hi:[1,1,0]
	v_pk_fma_f32 v[76:77], v[18:19], v[18:19], v[78:79] op_sel_hi:[1,1,0]
	v_pk_add_f32 v[66:67], v[68:69], v[68:69] op_sel_hi:[0,1]
	v_pk_add_f32 v[64:65], v[64:65], v[64:65] op_sel_hi:[0,1]
	v_pk_mul_f32 v[80:81], v[14:15], v[14:15]
	v_pk_mul_f32 v[82:83], v[12:13], v[12:13]
	v_mul_f32_e32 v72, v8, v8
	v_mul_f32_e32 v76, v9, v9
	v_mul_f32_e32 v66, v10, v10
	v_mul_f32_e32 v64, v11, v11
	v_pk_mov_b32 v[78:79], v[82:83], v[80:81] op_sel:[1,0]
	v_mov_b32_e32 v83, v81
	v_pk_add_f32 v[68:69], v[72:73], v[76:77]
	v_pk_add_f32 v[64:65], v[66:67], v[64:65]
	v_pk_add_f32 v[70:71], v[78:79], v[82:83]
	v_pk_add_f32 v[64:65], v[68:69], v[64:65]
	v_pk_add_f32 v[72:73], v[70:71], v[70:71] op_sel_hi:[0,1]
	v_pk_add_f32 v[74:75], v[64:65], v[64:65] op_sel_hi:[0,1]
	v_fmamk_f32 v4, v87, 0xba000000, v4
	v_fmac_f32_e32 v6, 0xba000000, v87
	v_fmamk_f32 v5, v87, 0xba000000, v5
	v_fmamk_f32 v7, v87, 0xba000000, v7
	v_mul_f32_e32 v84, v4, v4
	v_mul_f32_e32 v86, v6, v6
	v_pk_fma_f32 v[80:81], v[4:5], v[4:5], v[84:85] op_sel_hi:[1, 1, 0]
	v_pk_fma_f32 v[84:85], v[6:7], v[6:7], v[86:87] op_sel_hi:[1, 1, 0]
	v_fmamk_f32 v77, v87, 0xba000000, v3
	v_fmamk_f32 v76, v87, 0xba000000, v2
	v_fmamk_f32 v1, v87, 0xba000000, v1
	v_fmac_f32_e32 v0, 0xba000000, v87
	v_mul_f32_e32 v80, v0, v0
	v_mul_f32_e32 v84, v1, v1
	v_mul_f32_e32 v72, v76, v76
	v_mul_f32_e32 v74, v77, v77
	v_pk_add_f32 v[2:3], v[80:81], v[84:85]
	v_pk_add_f32 v[72:73], v[72:73], v[74:75]
	s_nop 0
	v_pk_add_f32 v[2:3], v[2:3], v[72:73]
	s_nop 0
	v_add_f32_e32 v2, v2, v3
	ds_bpermute_b32 v3, v56, v2
	s_waitcnt lgkmcnt(0)
; __device__ __forceinline__ unsigned pk2(float lo, float hi) { return f2bf(lo) | (f2bf(hi) << 16); }
; __device__ __forceinline__ void ln_row(const float* xin, float* yout, bf16_t* ybf, const float* g, const float* b, int lane) {
;     ...
;     const float rstd = 1.f / sqrtf(wave_sum(s2, lane) * (1.f / DM) + LN_EPS);
;     f32x4* yo = (f32x4*)yout + lane; u32x2* o8 = (u32x2*)ybf + lane;
; #pragma unroll
;     for (int j = 0; j < 8; ++j) { const f32x4 gg = ((const f32x4*)g)[lane + 64 * j], bb = ((const f32x4*)b)[lane + 64 * j];
;         const f32x4 y = v[j] * rstd * gg + bb; yo[64 * j] = y; if (ybf) { u32x2 w; w.x = pk2(y[0], y[1]); w.y = pk2(y[2], y[3]); o8[64 * j] = w; } }
	v_add_f32_e32 v2, v2, v3
	ds_bpermute_b32 v3, v57, v2
	s_waitcnt lgkmcnt(0)
	v_add_f32_e32 v2, v2, v3
	ds_bpermute_b32 v3, v58, v2
	s_waitcnt lgkmcnt(0)
	v_add_f32_e32 v2, v2, v3
	ds_bpermute_b32 v3, v59, v2
	s_waitcnt lgkmcnt(0)
	v_add_f32_e32 v2, v2, v3
	ds_bpermute_b32 v3, v60, v2
	s_waitcnt lgkmcnt(0)
	v_add_f32_e32 v2, v2, v3
	ds_bpermute_b32 v3, v61, v2
	s_waitcnt lgkmcnt(0)
	v_add_f32_e32 v2, v2, v3
	v_fmamk_f32 v2, v2, 0x3a000000, v62
	v_mul_f32_e32 v3, 0x4f800000, v2
	v_cmp_gt_f32_e32 vcc, s5, v2
	s_nop 1
	v_cndmask_b32_e32 v2, v2, v3, vcc
	v_sqrt_f32_e32 v3, v2
	s_nop 0
	v_add_u32_e32 v72, -1, v3
	v_add_u32_e32 v73, 1, v3
	v_fma_f32 v74, -v72, v3, v2
	v_fma_f32 v75, -v73, v3, v2
	v_cmp_ge_f32_e64 s[0:1], 0, v74
	s_nop 1
	v_cndmask_b32_e64 v3, v3, v72, s[0:1]
	v_cmp_lt_f32_e64 s[0:1], 0, v75
	s_nop 1
	v_cndmask_b32_e64 v3, v3, v73, s[0:1]
	v_mul_f32_e32 v72, 0x37800000, v3
	v_cndmask_b32_e32 v3, v3, v72, vcc
	v_cmp_class_f32_e32 vcc, v2, v63
	s_nop 1
	v_cndmask_b32_e32 v2, v3, v2, vcc
	v_div_scale_f32 v3, s[0:1], v2, v2, 1.0
	v_rcp_f32_e32 v72, v3
	v_div_scale_f32 v73, vcc, 1.0, v2, 1.0
	v_fma_f32 v74, -v3, v72, 1.0
	v_fmac_f32_e32 v72, v74, v72
	v_mul_f32_e32 v74, v73, v72
	v_fma_f32 v75, -v3, v74, v73
	v_fmac_f32_e32 v74, v75, v72
	v_fma_f32 v3, -v3, v74, v73
	v_div_fmas_f32 v3, v3, v72, v74
	v_div_fixup_f32 v72, v3, v2, 1.0
	v_pk_mul_f32 v[2:3], v[28:29], v[72:73] op_sel_hi:[1, 0]
	v_pk_mul_f32 v[28:29], v[30:31], v[72:73] op_sel_hi:[1, 0]
	v_pk_mul_f32 v[24:25], v[24:25], v[72:73] op_sel_hi:[1, 0]
	v_pk_fma_f32 v[30:31], v[102:103], v[28:29], v[134:135]
	v_pk_fma_f32 v[28:29], v[100:101], v[2:3], v[132:133]
	global_store_dwordx4 v[54:55], v[28:31], off offset:-3072 nt
	s_nop 1
	s_nop 0
	v_pk_mul_f32 v[2:3], v[26:27], v[72:73] op_sel_hi:[1, 0]
	v_pk_mul_f32 v[20:21], v[20:21], v[72:73] op_sel_hi:[1, 0]
	v_pk_mul_f32 v[16:17], v[16:17], v[72:73] op_sel_hi:[1, 0]
	v_pk_mul_f32 v[8:9], v[8:9], v[72:73] op_sel_hi:[1, 0]
	v_pk_mul_f32 v[12:13], v[12:13], v[72:73] op_sel_hi:[1, 0]
	v_pk_mul_f32 v[6:7], v[6:7], v[72:73] op_sel_hi:[1, 0]
	v_pk_mul_f32 v[0:1], v[0:1], v[72:73] op_sel_hi:[1, 0]
	v_pk_fma_f32 v[24:25], v[104:105], v[24:25], v[136:137]
	v_pk_fma_f32 v[26:27], v[106:107], v[2:3], v[138:139]
	global_store_dwordx4 v[54:55], v[24:27], off offset:-2048 nt
	s_nop 1
	s_nop 0
	v_pk_mul_f32 v[2:3], v[22:23], v[72:73] op_sel_hi:[1, 0]
	v_pk_fma_f32 v[20:21], v[108:109], v[20:21], v[140:141]
	v_pk_fma_f32 v[22:23], v[110:111], v[2:3], v[142:143]
	global_store_dwordx4 v[54:55], v[20:23], off offset:-1024 nt
	s_nop 1
	s_nop 0
	v_pk_mul_f32 v[2:3], v[18:19], v[72:73] op_sel_hi:[1, 0]
	v_pk_fma_f32 v[16:17], v[112:113], v[16:17], v[144:145]
	v_pk_fma_f32 v[18:19], v[114:115], v[2:3], v[146:147]
	global_store_dwordx4 v[52:53], v[16:19], off offset:-4096 nt
	s_nop 1
	s_nop 0
	v_pk_mul_f32 v[2:3], v[10:11], v[72:73] op_sel_hi:[1, 0]
	v_pk_fma_f32 v[8:9], v[116:117], v[8:9], v[148:149]
	v_pk_fma_f32 v[10:11], v[118:119], v[2:3], v[150:151]
	global_store_dwordx4 v[52:53], v[8:11], off offset:-3072 nt
	s_nop 1
	s_nop 0
	v_pk_mul_f32 v[2:3], v[14:15], v[72:73] op_sel_hi:[1, 0]
	v_pk_fma_f32 v[8:9], v[120:121], v[12:13], v[152:153]
	v_pk_fma_f32 v[10:11], v[122:123], v[2:3], v[154:155]
	global_store_dwordx4 v[52:53], v[8:11], off offset:-2048 nt
	s_nop 1
	s_nop 0
	v_pk_mul_f32 v[2:3], v[4:5], v[72:73] op_sel_hi:[1, 0]
	v_pk_fma_f32 v[4:5], v[126:127], v[6:7], v[158:159]
	v_pk_fma_f32 v[2:3], v[124:125], v[2:3], v[156:157]
	global_store_dwordx4 v[52:53], v[2:5], off offset:-1024 nt
	s_nop 1
	s_nop 0
	v_pk_mul_f32 v[10:11], v[76:77], v[72:73] op_sel_hi:[1, 0]
	v_pk_fma_f32 v[0:1], v[128:129], v[0:1], v[160:161]
	v_pk_fma_f32 v[2:3], v[130:131], v[10:11], v[162:163]
	global_store_dwordx4 v[52:53], v[0:3], off nt
	s_nop 1
	v_lshl_add_u64 v[52:53], v[52:53], 0, s[2:3]
	s_cbranch_scc0 .LBB0_1298
